# norm loops (N1 layer 1, N3 both variants): all 16 row loads of a trip issued back to back instead of one load per vmcnt(0)
# baseline (speedup 1.0000x reference)
.LBB0_122:
	v_lshl_add_u64 v[36:37], s[40:41], 0, v[176:177]
	v_add_co_u32_e32 v36, vcc, 0x4000000, v36
	s_add_i32 s3, s72, s22
	s_nop 0
	v_addc_co_u32_e32 v37, vcc, 0, v37, vcc
	s_add_i32 s0, s3, 1
	s_ashr_i32 s1, s0, 31
	s_lshl_b64 s[42:43], s[0:1], 11
	s_add_i32 s0, s3, 2
	s_ashr_i32 s1, s0, 31
	s_lshl_b64 s[38:39], s[0:1], 11
	s_add_i32 s0, s3, 3
	s_ashr_i32 s1, s0, 31
	s_lshl_b64 s[34:35], s[0:1], 11
	s_add_i32 s22, s22, 4
	s_add_u32 s40, s40, 0x2000
	s_addc_u32 s41, s41, 0
	v_lshl_add_u64 v[152:153], v[16:17], 0, s[42:43]
	v_lshl_add_u64 v[154:155], v[16:17], 0, s[38:39]
	v_lshl_add_u64 v[156:157], v[16:17], 0, s[34:35]
	global_load_dwordx2 v[120:121], v[36:37], off
	global_load_dwordx2 v[122:123], v[36:37], off offset:512
	global_load_dwordx2 v[124:125], v[36:37], off offset:1024
	global_load_dwordx2 v[126:127], v[36:37], off offset:1536
	global_load_dwordx2 v[128:129], v[152:153], off
	global_load_dwordx2 v[130:131], v[152:153], off offset:512
	global_load_dwordx2 v[132:133], v[152:153], off offset:1024
	global_load_dwordx2 v[134:135], v[152:153], off offset:1536
	global_load_dwordx2 v[136:137], v[154:155], off
	global_load_dwordx2 v[138:139], v[154:155], off offset:512
	global_load_dwordx2 v[140:141], v[154:155], off offset:1024
	global_load_dwordx2 v[142:143], v[154:155], off offset:1536
	global_load_dwordx2 v[144:145], v[156:157], off
	global_load_dwordx2 v[146:147], v[156:157], off offset:512
	global_load_dwordx2 v[148:149], v[156:157], off offset:1024
	global_load_dwordx2 v[150:151], v[156:157], off offset:1536
	s_waitcnt vmcnt(0)
	v_mov_b32_e32 v38, v120
	v_mov_b32_e32 v39, v121
	v_cvt_f32_f16_e32 v80, v38
	v_cvt_f32_f16_sdwa v81, v38 dst_sel:DWORD dst_unused:UNUSED_PAD src0_sel:WORD_1
	v_cvt_f32_f16_e32 v82, v39
	v_cvt_f32_f16_sdwa v83, v39 dst_sel:DWORD dst_unused:UNUSED_PAD src0_sel:WORD_1
	v_mov_b32_e32 v38, v122
	v_mov_b32_e32 v39, v123
	v_mov_b32_e32 v110, v81
	v_mov_b32_e32 v108, v80
	v_mov_b32_e32 v111, v83
	v_mov_b32_e32 v109, v82
	v_pk_mul_f32 v[110:111], v[110:111], v[110:111]
	v_cvt_f32_f16_e32 v76, v38
	v_cvt_f32_f16_sdwa v77, v38 dst_sel:DWORD dst_unused:UNUSED_PAD src0_sel:WORD_1
	v_cvt_f32_f16_e32 v78, v39
	v_cvt_f32_f16_sdwa v79, v39 dst_sel:DWORD dst_unused:UNUSED_PAD src0_sel:WORD_1
	v_mov_b32_e32 v38, v124
	v_mov_b32_e32 v39, v125
	v_mov_b32_e32 v112, v77
	v_mov_b32_e32 v36, v126
	v_mov_b32_e32 v37, v127
	v_mov_b32_e32 v113, v79
	v_pk_fma_f32 v[108:109], v[108:109], v[108:109], v[110:111]
	v_mov_b32_e32 v110, v76
	v_mov_b32_e32 v111, v78
	v_pk_mul_f32 v[112:113], v[112:113], v[112:113]
	v_pk_add_f32 v[108:109], v[108:109], v[108:109] op_sel:[0,1] op_sel_hi:[1,0]
	v_pk_fma_f32 v[110:111], v[110:111], v[110:111], v[112:113]
	v_cvt_f32_f16_e32 v72, v38
	v_cvt_f32_f16_sdwa v73, v38 dst_sel:DWORD dst_unused:UNUSED_PAD src0_sel:WORD_1
	v_cvt_f32_f16_e32 v68, v36
	v_cvt_f32_f16_sdwa v69, v36 dst_sel:DWORD dst_unused:UNUSED_PAD src0_sel:WORD_1
	v_cvt_f32_f16_e32 v70, v37
	v_cvt_f32_f16_sdwa v71, v37 dst_sel:DWORD dst_unused:UNUSED_PAD src0_sel:WORD_1
	v_lshl_add_u64 v[36:37], v[16:17], 0, s[42:43]
	v_cvt_f32_f16_e32 v74, v39
	v_cvt_f32_f16_sdwa v75, v39 dst_sel:DWORD dst_unused:UNUSED_PAD src0_sel:WORD_1
	v_mov_b32_e32 v38, v128
	v_mov_b32_e32 v39, v129
	v_mul_f32_e32 v100, v73, v73
	v_pk_fma_f32 v[112:113], v[72:73], v[72:73], v[100:101] op_sel_hi:[1,1,0]
	v_mul_f32_e32 v100, v75, v75
	v_pk_add_f32 v[110:111], v[110:111], v[110:111] op_sel:[0,1] op_sel_hi:[1,0]
	v_pk_fma_f32 v[114:115], v[74:75], v[74:75], v[100:101] op_sel_hi:[1,1,0]
	v_pk_mul_f32 v[116:117], v[68:69], v[68:69]
	v_pk_mul_f32 v[118:119], v[70:71], v[70:71]
	v_mov_b32_e32 v109, v116
	v_mov_b32_e32 v111, v117
	v_mov_b32_e32 v113, v118
	v_mov_b32_e32 v115, v119
	v_pk_add_f32 v[108:109], v[108:109], v[110:111]
	v_pk_add_f32 v[110:111], v[112:113], v[114:115]
	v_cvt_f32_f16_e32 v96, v38
	v_cvt_f32_f16_sdwa v97, v38 dst_sel:DWORD dst_unused:UNUSED_PAD src0_sel:WORD_1
	v_cvt_f32_f16_e32 v98, v39
	v_cvt_f32_f16_sdwa v99, v39 dst_sel:DWORD dst_unused:UNUSED_PAD src0_sel:WORD_1
	v_mov_b32_e32 v38, v130
	v_mov_b32_e32 v39, v131
	v_pk_add_f32 v[108:109], v[108:109], v[110:111]
	v_cvt_f32_f16_e32 v92, v38
	v_cvt_f32_f16_sdwa v93, v38 dst_sel:DWORD dst_unused:UNUSED_PAD src0_sel:WORD_1
	v_cvt_f32_f16_e32 v94, v39
	v_cvt_f32_f16_sdwa v95, v39 dst_sel:DWORD dst_unused:UNUSED_PAD src0_sel:WORD_1
	v_mov_b32_e32 v38, v132
	v_mov_b32_e32 v39, v133
	v_add_f32_e32 v100, v108, v109
	v_mov_b32_e32 v36, v134
	v_mov_b32_e32 v37, v135
	ds_bpermute_b32 v107, v101, v100
	s_waitcnt lgkmcnt(0)
	v_add_f32_e32 v100, v100, v107
	ds_bpermute_b32 v107, v102, v100
	s_waitcnt lgkmcnt(0)
	v_add_f32_e32 v100, v100, v107
	ds_bpermute_b32 v107, v103, v100
	s_waitcnt lgkmcnt(0)
	v_add_f32_e32 v100, v100, v107
	ds_bpermute_b32 v107, v104, v100
	s_waitcnt lgkmcnt(0)
	v_add_f32_e32 v100, v100, v107
	ds_bpermute_b32 v107, v105, v100
	s_waitcnt lgkmcnt(0)
	v_add_f32_e32 v100, v100, v107
	ds_bpermute_b32 v107, v106, v100
	s_waitcnt lgkmcnt(0)
	v_add_f32_e32 v100, v100, v107
	v_fmamk_f32 v100, v100, 0x3a800000, v228
	v_cmp_gt_f32_e32 vcc, s89, v100
	v_mul_f32_e32 v107, 0x4f800000, v100
	v_cvt_f32_f16_e32 v88, v38
	v_cvt_f32_f16_sdwa v89, v38 dst_sel:DWORD dst_unused:UNUSED_PAD src0_sel:WORD_1
	v_cvt_f32_f16_e32 v84, v36
	v_cvt_f32_f16_sdwa v85, v36 dst_sel:DWORD dst_unused:UNUSED_PAD src0_sel:WORD_1
	v_cvt_f32_f16_e32 v86, v37
	v_cvt_f32_f16_sdwa v87, v37 dst_sel:DWORD dst_unused:UNUSED_PAD src0_sel:WORD_1
	v_lshl_add_u64 v[36:37], v[16:17], 0, s[38:39]
	v_cvt_f32_f16_e32 v90, v39
	v_cvt_f32_f16_sdwa v91, v39 dst_sel:DWORD dst_unused:UNUSED_PAD src0_sel:WORD_1
	v_mov_b32_e32 v38, v136
	v_mov_b32_e32 v39, v137
	v_cndmask_b32_e32 v100, v100, v107, vcc
	v_sqrt_f32_e32 v107, v100
	v_cvt_f32_f16_e32 v64, v38
	v_cvt_f32_f16_sdwa v65, v38 dst_sel:DWORD dst_unused:UNUSED_PAD src0_sel:WORD_1
	v_cvt_f32_f16_e32 v66, v39
	v_cvt_f32_f16_sdwa v67, v39 dst_sel:DWORD dst_unused:UNUSED_PAD src0_sel:WORD_1
	v_mov_b32_e32 v38, v138
	v_mov_b32_e32 v39, v139
	v_add_u32_e32 v108, -1, v107
	v_fma_f32 v109, -v108, v107, v100
	v_cmp_ge_f32_e64 s[0:1], 0, v109
	v_add_u32_e32 v109, 1, v107
	v_cvt_f32_f16_e32 v60, v38
	v_cvt_f32_f16_sdwa v61, v38 dst_sel:DWORD dst_unused:UNUSED_PAD src0_sel:WORD_1
	v_cvt_f32_f16_e32 v62, v39
	v_cvt_f32_f16_sdwa v63, v39 dst_sel:DWORD dst_unused:UNUSED_PAD src0_sel:WORD_1
	v_mov_b32_e32 v38, v140
	v_mov_b32_e32 v39, v141
	v_cndmask_b32_e64 v108, v107, v108, s[0:1]
	v_mov_b32_e32 v36, v142
	v_mov_b32_e32 v37, v143
	v_fma_f32 v107, -v109, v107, v100
	v_cmp_lt_f32_e64 s[0:1], 0, v107
	v_cvt_f32_f16_e32 v56, v38
	v_cvt_f32_f16_sdwa v57, v38 dst_sel:DWORD dst_unused:UNUSED_PAD src0_sel:WORD_1
	v_cvt_f32_f16_e32 v52, v36
	v_cvt_f32_f16_sdwa v53, v36 dst_sel:DWORD dst_unused:UNUSED_PAD src0_sel:WORD_1
	v_cvt_f32_f16_e32 v54, v37
	v_cvt_f32_f16_sdwa v55, v37 dst_sel:DWORD dst_unused:UNUSED_PAD src0_sel:WORD_1
	v_lshl_add_u64 v[36:37], v[16:17], 0, s[34:35]
	v_cvt_f32_f16_e32 v58, v39
	v_cvt_f32_f16_sdwa v59, v39 dst_sel:DWORD dst_unused:UNUSED_PAD src0_sel:WORD_1
	v_mov_b32_e32 v38, v144
	v_mov_b32_e32 v39, v145
	v_cndmask_b32_e64 v107, v108, v109, s[0:1]
	v_mul_f32_e32 v108, 0x37800000, v107
	v_cndmask_b32_e32 v107, v107, v108, vcc
	v_cmp_class_f32_e32 vcc, v100, v229
	v_cvt_f32_f16_e32 v48, v38
	v_cvt_f32_f16_sdwa v49, v38 dst_sel:DWORD dst_unused:UNUSED_PAD src0_sel:WORD_1
	v_cvt_f32_f16_e32 v50, v39
	v_cvt_f32_f16_sdwa v51, v39 dst_sel:DWORD dst_unused:UNUSED_PAD src0_sel:WORD_1
	v_mov_b32_e32 v38, v146
	v_mov_b32_e32 v39, v147
	v_cndmask_b32_e32 v100, v107, v100, vcc
	v_div_scale_f32 v107, s[0:1], v100, v100, 1.0
	v_rcp_f32_e32 v108, v107
	v_cvt_f32_f16_e32 v44, v38
	v_cvt_f32_f16_sdwa v45, v38 dst_sel:DWORD dst_unused:UNUSED_PAD src0_sel:WORD_1
	v_cvt_f32_f16_e32 v46, v39
	v_cvt_f32_f16_sdwa v47, v39 dst_sel:DWORD dst_unused:UNUSED_PAD src0_sel:WORD_1
	v_mov_b32_e32 v38, v148
	v_mov_b32_e32 v39, v149
	v_fma_f32 v109, -v107, v108, 1.0
	v_fmac_f32_e32 v108, v109, v108
	v_div_scale_f32 v109, vcc, 1.0, v100, 1.0
	v_mul_f32_e32 v110, v109, v108
	v_fma_f32 v111, -v107, v110, v109
	v_fmac_f32_e32 v110, v111, v108
	v_fma_f32 v107, -v107, v110, v109
	v_div_fmas_f32 v107, v107, v108, v110
	v_div_fixup_f32 v100, v107, v100, 1.0
	v_pk_mul_f32 v[80:81], v[80:81], v[100:101] op_sel_hi:[1,0]
	v_pk_mul_f32 v[82:83], v[82:83], v[100:101] op_sel_hi:[1,0]
	v_lshl_add_u64 v[108:109], s[36:37], 0, v[176:177]
	v_pk_fma_f32 v[82:83], v[20:21], v[82:83], v[2:3]
	v_pk_fma_f32 v[80:81], v[22:23], v[80:81], v[0:1]
	v_pk_mul_f32 v[72:73], v[72:73], v[100:101] op_sel_hi:[1,0]
	v_pk_mul_f32 v[74:75], v[74:75], v[100:101] op_sel_hi:[1,0]
	v_pk_mul_f32 v[68:69], v[68:69], v[100:101] op_sel_hi:[1,0]
	v_pk_mul_f32 v[70:71], v[70:71], v[100:101] op_sel_hi:[1,0]
	v_cvt_pk_bf16_f32 v80, v80, v81
	v_cvt_pk_bf16_f32 v81, v82, v83
	v_add_co_u32_e32 v82, vcc, s7, v108
	v_pk_fma_f32 v[74:75], v[28:29], v[74:75], v[10:11]
	v_pk_fma_f32 v[72:73], v[30:31], v[72:73], v[8:9]
	v_pk_fma_f32 v[70:71], v[32:33], v[70:71], v[14:15]
	v_pk_fma_f32 v[68:69], v[34:35], v[68:69], v[12:13]
	v_addc_co_u32_e32 v83, vcc, 0, v109, vcc
	v_cvt_pk_bf16_f32 v72, v72, v73
	v_cvt_pk_bf16_f32 v73, v74, v75
	v_cvt_pk_bf16_f32 v68, v68, v69
	v_cvt_pk_bf16_f32 v69, v70, v71
	v_mov_b32_e32 v70, v97
	v_mov_b32_e32 v71, v99
	v_pk_mul_f32 v[76:77], v[76:77], v[100:101] op_sel_hi:[1,0]
	v_pk_mul_f32 v[78:79], v[78:79], v[100:101] op_sel_hi:[1,0]
	v_pk_mul_f32 v[70:71], v[70:71], v[70:71]
	v_pk_fma_f32 v[78:79], v[24:25], v[78:79], v[6:7]
	v_pk_fma_f32 v[76:77], v[26:27], v[76:77], v[4:5]
	v_mul_f32_e32 v74, v91, v91
	v_cvt_pk_bf16_f32 v76, v76, v77
	v_cvt_pk_bf16_f32 v77, v78, v79
	v_pk_fma_f32 v[74:75], v[90:91], v[90:91], v[74:75] op_sel_hi:[1,1,0]
	v_pk_mul_f32 v[78:79], v[86:87], v[86:87]
	s_add_u32 s36, s36, 0x2000
	v_mov_b32_e32 v75, v79
	s_addc_u32 s37, s37, 0
	s_cmp_ge_i32 s22, s10
	v_cvt_f32_f16_e32 v40, v38
	v_cvt_f32_f16_sdwa v41, v38 dst_sel:DWORD dst_unused:UNUSED_PAD src0_sel:WORD_1
	v_cvt_f32_f16_e32 v42, v39
	v_cvt_f32_f16_sdwa v43, v39 dst_sel:DWORD dst_unused:UNUSED_PAD src0_sel:WORD_1
	v_mov_b32_e32 v38, v150
	v_mov_b32_e32 v39, v151
	v_cvt_f32_f16_e32 v36, v38
	flat_store_dwordx2 v[82:83], v[72:73] offset:1024
	flat_store_dwordx2 v[82:83], v[68:69] offset:1536
	v_mov_b32_e32 v68, v96
	v_mov_b32_e32 v69, v98
	v_mov_b32_e32 v72, v93
	v_mov_b32_e32 v73, v95
	v_pk_fma_f32 v[68:69], v[68:69], v[68:69], v[70:71]
	v_mov_b32_e32 v70, v92
	v_mov_b32_e32 v71, v94
	v_pk_mul_f32 v[72:73], v[72:73], v[72:73]
	flat_store_dwordx2 v[82:83], v[76:77] offset:512
	v_pk_fma_f32 v[70:71], v[70:71], v[70:71], v[72:73]
	v_mul_f32_e32 v72, v89, v89
	v_pk_add_f32 v[68:69], v[68:69], v[68:69] op_sel:[0,1] op_sel_hi:[1,0]
	v_pk_add_f32 v[70:71], v[70:71], v[70:71] op_sel:[0,1] op_sel_hi:[1,0]
	v_pk_fma_f32 v[72:73], v[88:89], v[88:89], v[72:73] op_sel_hi:[1,1,0]
	v_pk_mul_f32 v[76:77], v[84:85], v[84:85]
	v_mov_b32_e32 v73, v78
	v_mov_b32_e32 v69, v76
	v_mov_b32_e32 v71, v77
	v_pk_add_f32 v[68:69], v[68:69], v[70:71]
	v_pk_add_f32 v[70:71], v[72:73], v[74:75]
	flat_store_dwordx2 v[82:83], v[80:81]
	v_pk_add_f32 v[68:69], v[68:69], v[70:71]
	v_pk_mul_f32 v[76:77], v[52:53], v[52:53]
	v_add_f32_e32 v68, v68, v69
	ds_bpermute_b32 v69, v101, v68
	v_pk_mul_f32 v[78:79], v[54:55], v[54:55]
	v_cvt_f32_f16_sdwa v37, v38 dst_sel:DWORD dst_unused:UNUSED_PAD src0_sel:WORD_1
	v_cvt_f32_f16_e32 v38, v39
	v_cvt_f32_f16_sdwa v39, v39 dst_sel:DWORD dst_unused:UNUSED_PAD src0_sel:WORD_1
	s_waitcnt lgkmcnt(0)
	v_add_f32_e32 v68, v68, v69
	ds_bpermute_b32 v69, v102, v68
	s_waitcnt lgkmcnt(0)
	v_add_f32_e32 v68, v68, v69
	ds_bpermute_b32 v69, v103, v68
	s_waitcnt lgkmcnt(0)
	v_add_f32_e32 v68, v68, v69
	ds_bpermute_b32 v69, v104, v68
	s_waitcnt lgkmcnt(0)
	v_add_f32_e32 v68, v68, v69
	ds_bpermute_b32 v69, v105, v68
	s_waitcnt lgkmcnt(0)
	v_add_f32_e32 v68, v68, v69
	ds_bpermute_b32 v69, v106, v68
	s_waitcnt lgkmcnt(0)
	v_add_f32_e32 v68, v68, v69
	v_fmamk_f32 v68, v68, 0x3a800000, v228
	v_cmp_gt_f32_e32 vcc, s89, v68
	v_mul_f32_e32 v69, 0x4f800000, v68
	s_nop 0
	v_cndmask_b32_e32 v68, v68, v69, vcc
	v_sqrt_f32_e32 v69, v68
	s_nop 0
	v_add_u32_e32 v70, -1, v69
	v_fma_f32 v71, -v70, v69, v68
	v_cmp_ge_f32_e64 s[0:1], 0, v71
	v_add_u32_e32 v71, 1, v69
	s_nop 0
	v_cndmask_b32_e64 v70, v69, v70, s[0:1]
	v_fma_f32 v69, -v71, v69, v68
	v_cmp_lt_f32_e64 s[0:1], 0, v69
	s_nop 1
	v_cndmask_b32_e64 v69, v70, v71, s[0:1]
	v_mul_f32_e32 v70, 0x37800000, v69
	v_cndmask_b32_e32 v69, v69, v70, vcc
	v_cmp_class_f32_e32 vcc, v68, v229
	s_nop 1
	v_cndmask_b32_e32 v68, v69, v68, vcc
	v_div_scale_f32 v69, s[0:1], v68, v68, 1.0
	v_rcp_f32_e32 v70, v69
	s_nop 0
	v_fma_f32 v71, -v69, v70, 1.0
	v_fmac_f32_e32 v70, v71, v70
	v_div_scale_f32 v71, vcc, 1.0, v68, 1.0
	v_mul_f32_e32 v72, v71, v70
	v_fma_f32 v73, -v69, v72, v71
	v_fmac_f32_e32 v72, v73, v70
	v_fma_f32 v69, -v69, v72, v71
	v_div_fmas_f32 v69, v69, v70, v72
	v_div_fixup_f32 v68, v69, v68, 1.0
	v_pk_mul_f32 v[72:73], v[96:97], v[68:69] op_sel_hi:[1,0]
	v_pk_mul_f32 v[74:75], v[98:99], v[68:69] op_sel_hi:[1,0]
	v_pk_fma_f32 v[72:73], v[22:23], v[72:73], v[0:1]
	v_pk_fma_f32 v[74:75], v[20:21], v[74:75], v[2:3]
	v_lshl_add_u64 v[70:71], v[18:19], 0, s[42:43]
	v_cvt_pk_bf16_f32 v72, v72, v73
	v_cvt_pk_bf16_f32 v73, v74, v75
	flat_store_dwordx2 v[70:71], v[72:73]
	v_pk_mul_f32 v[72:73], v[92:93], v[68:69] op_sel_hi:[1,0]
	v_pk_mul_f32 v[74:75], v[94:95], v[68:69] op_sel_hi:[1,0]
	v_pk_fma_f32 v[72:73], v[26:27], v[72:73], v[4:5]
	v_pk_fma_f32 v[74:75], v[24:25], v[74:75], v[6:7]
	v_cvt_pk_bf16_f32 v72, v72, v73
	v_cvt_pk_bf16_f32 v73, v74, v75
	flat_store_dwordx2 v[70:71], v[72:73] offset:512
	v_pk_mul_f32 v[72:73], v[88:89], v[68:69] op_sel_hi:[1,0]
	v_pk_mul_f32 v[74:75], v[90:91], v[68:69] op_sel_hi:[1,0]
	v_pk_fma_f32 v[72:73], v[30:31], v[72:73], v[8:9]
	v_pk_fma_f32 v[74:75], v[28:29], v[74:75], v[10:11]
	v_cvt_pk_bf16_f32 v72, v72, v73
	v_cvt_pk_bf16_f32 v73, v74, v75
	flat_store_dwordx2 v[70:71], v[72:73] offset:1024
	v_pk_mul_f32 v[72:73], v[84:85], v[68:69] op_sel_hi:[1,0]
	v_pk_mul_f32 v[68:69], v[86:87], v[68:69] op_sel_hi:[1,0]
	v_pk_fma_f32 v[72:73], v[34:35], v[72:73], v[12:13]
	v_pk_fma_f32 v[68:69], v[32:33], v[68:69], v[14:15]
	v_cvt_pk_bf16_f32 v72, v72, v73
	v_cvt_pk_bf16_f32 v73, v68, v69
	flat_store_dwordx2 v[70:71], v[72:73] offset:1536
	v_mov_b32_e32 v70, v65
	v_mov_b32_e32 v71, v67
	v_mov_b32_e32 v68, v64
	v_mov_b32_e32 v69, v66
	v_pk_mul_f32 v[70:71], v[70:71], v[70:71]
	v_mov_b32_e32 v72, v61
	v_mov_b32_e32 v73, v63
	v_pk_fma_f32 v[68:69], v[68:69], v[68:69], v[70:71]
	v_mov_b32_e32 v70, v60
	v_mov_b32_e32 v71, v62
	v_pk_mul_f32 v[72:73], v[72:73], v[72:73]
	v_mul_f32_e32 v74, v59, v59
	v_pk_fma_f32 v[70:71], v[70:71], v[70:71], v[72:73]
	v_mul_f32_e32 v72, v57, v57
	v_pk_add_f32 v[68:69], v[68:69], v[68:69] op_sel:[0,1] op_sel_hi:[1,0]
	v_pk_add_f32 v[70:71], v[70:71], v[70:71] op_sel:[0,1] op_sel_hi:[1,0]
	v_pk_fma_f32 v[72:73], v[56:57], v[56:57], v[72:73] op_sel_hi:[1,1,0]
	v_pk_fma_f32 v[74:75], v[58:59], v[58:59], v[74:75] op_sel_hi:[1,1,0]
	v_mov_b32_e32 v69, v76
	v_mov_b32_e32 v71, v77
	v_mov_b32_e32 v73, v78
	v_mov_b32_e32 v75, v79
	v_pk_add_f32 v[68:69], v[68:69], v[70:71]
	v_pk_add_f32 v[70:71], v[72:73], v[74:75]
	s_nop 0
	v_pk_add_f32 v[68:69], v[68:69], v[70:71]
	s_nop 0
	v_add_f32_e32 v68, v68, v69
	ds_bpermute_b32 v69, v101, v68
	s_waitcnt lgkmcnt(0)
	v_add_f32_e32 v68, v68, v69
	ds_bpermute_b32 v69, v102, v68
	s_waitcnt lgkmcnt(0)
	v_add_f32_e32 v68, v68, v69
	ds_bpermute_b32 v69, v103, v68
	s_waitcnt lgkmcnt(0)
	v_add_f32_e32 v68, v68, v69
	ds_bpermute_b32 v69, v104, v68
	s_waitcnt lgkmcnt(0)
	v_add_f32_e32 v68, v68, v69
	ds_bpermute_b32 v69, v105, v68
	s_waitcnt lgkmcnt(0)
	v_add_f32_e32 v68, v68, v69
	ds_bpermute_b32 v69, v106, v68
	s_waitcnt lgkmcnt(0)
	v_add_f32_e32 v68, v68, v69
	v_fmamk_f32 v68, v68, 0x3a800000, v228
	v_cmp_gt_f32_e32 vcc, s89, v68
	v_mul_f32_e32 v69, 0x4f800000, v68
	s_nop 0
	v_cndmask_b32_e32 v68, v68, v69, vcc
	v_sqrt_f32_e32 v69, v68
	s_nop 0
	v_add_u32_e32 v70, -1, v69
	v_fma_f32 v71, -v70, v69, v68
	v_cmp_ge_f32_e64 s[0:1], 0, v71
	v_add_u32_e32 v71, 1, v69
	s_nop 0
	v_cndmask_b32_e64 v70, v69, v70, s[0:1]
	v_fma_f32 v69, -v71, v69, v68
	v_cmp_lt_f32_e64 s[0:1], 0, v69
	s_nop 1
	v_cndmask_b32_e64 v69, v70, v71, s[0:1]
	v_mul_f32_e32 v70, 0x37800000, v69
	v_cndmask_b32_e32 v69, v69, v70, vcc
	v_cmp_class_f32_e32 vcc, v68, v229
	s_nop 1
	v_cndmask_b32_e32 v68, v69, v68, vcc
	v_div_scale_f32 v69, s[0:1], v68, v68, 1.0
	v_rcp_f32_e32 v70, v69
	s_nop 0
	v_fma_f32 v71, -v69, v70, 1.0
	v_fmac_f32_e32 v70, v71, v70
	v_div_scale_f32 v71, vcc, 1.0, v68, 1.0
	v_mul_f32_e32 v72, v71, v70
	v_fma_f32 v73, -v69, v72, v71
	v_fmac_f32_e32 v72, v73, v70
	v_fma_f32 v69, -v69, v72, v71
	v_div_fmas_f32 v69, v69, v70, v72
	v_div_fixup_f32 v68, v69, v68, 1.0
	v_pk_mul_f32 v[56:57], v[56:57], v[68:69] op_sel_hi:[1,0]
	v_pk_mul_f32 v[58:59], v[58:59], v[68:69] op_sel_hi:[1,0]
	v_pk_mul_f32 v[52:53], v[52:53], v[68:69] op_sel_hi:[1,0]
	v_pk_mul_f32 v[54:55], v[54:55], v[68:69] op_sel_hi:[1,0]
	v_pk_fma_f32 v[58:59], v[28:29], v[58:59], v[10:11]
	v_pk_fma_f32 v[56:57], v[30:31], v[56:57], v[8:9]
	v_pk_fma_f32 v[54:55], v[32:33], v[54:55], v[14:15]
	v_pk_fma_f32 v[52:53], v[34:35], v[52:53], v[12:13]
	v_lshl_add_u64 v[70:71], v[18:19], 0, s[38:39]
	v_cvt_pk_bf16_f32 v56, v56, v57
	v_cvt_pk_bf16_f32 v57, v58, v59
	v_cvt_pk_bf16_f32 v52, v52, v53
	v_cvt_pk_bf16_f32 v53, v54, v55
	v_mov_b32_e32 v54, v49
	v_mov_b32_e32 v55, v51
	v_pk_mul_f32 v[60:61], v[60:61], v[68:69] op_sel_hi:[1,0]
	v_pk_mul_f32 v[62:63], v[62:63], v[68:69] op_sel_hi:[1,0]
	flat_store_dwordx2 v[70:71], v[56:57] offset:1024
	flat_store_dwordx2 v[70:71], v[52:53] offset:1536
	v_mov_b32_e32 v52, v48
	v_mov_b32_e32 v53, v50
	v_pk_mul_f32 v[54:55], v[54:55], v[54:55]
	v_mov_b32_e32 v56, v45
	v_mov_b32_e32 v57, v47
	v_pk_fma_f32 v[62:63], v[24:25], v[62:63], v[6:7]
	v_pk_fma_f32 v[60:61], v[26:27], v[60:61], v[4:5]
	v_pk_fma_f32 v[52:53], v[52:53], v[52:53], v[54:55]
	v_mov_b32_e32 v54, v44
	v_mov_b32_e32 v55, v46
	v_pk_mul_f32 v[56:57], v[56:57], v[56:57]
	v_cvt_pk_bf16_f32 v60, v60, v61
	v_cvt_pk_bf16_f32 v61, v62, v63
	v_pk_fma_f32 v[54:55], v[54:55], v[54:55], v[56:57]
	v_mul_f32_e32 v56, v41, v41
	v_mul_f32_e32 v58, v43, v43
	flat_store_dwordx2 v[70:71], v[60:61] offset:512
	v_pk_add_f32 v[52:53], v[52:53], v[52:53] op_sel:[0,1] op_sel_hi:[1,0]
	v_pk_add_f32 v[54:55], v[54:55], v[54:55] op_sel:[0,1] op_sel_hi:[1,0]
	v_pk_fma_f32 v[56:57], v[40:41], v[40:41], v[56:57] op_sel_hi:[1,1,0]
	v_pk_fma_f32 v[58:59], v[42:43], v[42:43], v[58:59] op_sel_hi:[1,1,0]
	v_pk_mul_f32 v[60:61], v[36:37], v[36:37]
	v_pk_mul_f32 v[62:63], v[38:39], v[38:39]
	v_mov_b32_e32 v53, v60
	v_mov_b32_e32 v55, v61
	v_mov_b32_e32 v57, v62
	v_mov_b32_e32 v59, v63
	v_pk_add_f32 v[52:53], v[52:53], v[54:55]
	v_pk_add_f32 v[54:55], v[56:57], v[58:59]
	v_pk_mul_f32 v[64:65], v[64:65], v[68:69] op_sel_hi:[1,0]
	v_pk_add_f32 v[52:53], v[52:53], v[54:55]
	v_pk_mul_f32 v[66:67], v[66:67], v[68:69] op_sel_hi:[1,0]
	v_add_f32_e32 v52, v52, v53
	ds_bpermute_b32 v53, v101, v52
	v_pk_fma_f32 v[66:67], v[20:21], v[66:67], v[2:3]
	v_pk_fma_f32 v[64:65], v[22:23], v[64:65], v[0:1]
	s_waitcnt lgkmcnt(0)
	v_add_f32_e32 v52, v52, v53
	ds_bpermute_b32 v53, v102, v52
	v_cvt_pk_bf16_f32 v64, v64, v65
	v_cvt_pk_bf16_f32 v65, v66, v67
	flat_store_dwordx2 v[70:71], v[64:65]
	s_waitcnt lgkmcnt(0)
	v_add_f32_e32 v52, v52, v53
	ds_bpermute_b32 v53, v103, v52
	s_waitcnt lgkmcnt(0)
	v_add_f32_e32 v52, v52, v53
	ds_bpermute_b32 v53, v104, v52
	s_waitcnt lgkmcnt(0)
	v_add_f32_e32 v52, v52, v53
	ds_bpermute_b32 v53, v105, v52
	s_waitcnt lgkmcnt(0)
	v_add_f32_e32 v52, v52, v53
	ds_bpermute_b32 v53, v106, v52
	s_waitcnt lgkmcnt(0)
	v_add_f32_e32 v52, v52, v53
	v_fmamk_f32 v52, v52, 0x3a800000, v228
	v_cmp_gt_f32_e32 vcc, s89, v52
	v_mul_f32_e32 v53, 0x4f800000, v52
	s_nop 0
	v_cndmask_b32_e32 v52, v52, v53, vcc
	v_sqrt_f32_e32 v53, v52
	s_nop 0
	v_add_u32_e32 v54, -1, v53
	v_fma_f32 v55, -v54, v53, v52
	v_cmp_ge_f32_e64 s[0:1], 0, v55
	v_add_u32_e32 v55, 1, v53
	s_nop 0
	v_cndmask_b32_e64 v54, v53, v54, s[0:1]
	v_fma_f32 v53, -v55, v53, v52
	v_cmp_lt_f32_e64 s[0:1], 0, v53
	s_nop 1
	v_cndmask_b32_e64 v53, v54, v55, s[0:1]
	v_mul_f32_e32 v54, 0x37800000, v53
	v_cndmask_b32_e32 v53, v53, v54, vcc
	v_cmp_class_f32_e32 vcc, v52, v229
	s_nop 1
	v_cndmask_b32_e32 v52, v53, v52, vcc
	v_div_scale_f32 v53, s[0:1], v52, v52, 1.0
	v_rcp_f32_e32 v54, v53
	s_nop 0
	v_fma_f32 v55, -v53, v54, 1.0
	v_fmac_f32_e32 v54, v55, v54
	v_div_scale_f32 v55, vcc, 1.0, v52, 1.0
	v_mul_f32_e32 v56, v55, v54
	v_fma_f32 v57, -v53, v56, v55
	v_fmac_f32_e32 v56, v57, v54
	v_fma_f32 v53, -v53, v56, v55
	v_div_fmas_f32 v53, v53, v54, v56
	v_div_fixup_f32 v52, v53, v52, 1.0
	v_pk_mul_f32 v[48:49], v[48:49], v[52:53] op_sel_hi:[1,0]
	v_pk_mul_f32 v[50:51], v[50:51], v[52:53] op_sel_hi:[1,0]
	v_pk_mul_f32 v[44:45], v[44:45], v[52:53] op_sel_hi:[1,0]
	v_pk_mul_f32 v[46:47], v[46:47], v[52:53] op_sel_hi:[1,0]
	v_pk_mul_f32 v[40:41], v[40:41], v[52:53] op_sel_hi:[1,0]
	v_pk_mul_f32 v[42:43], v[42:43], v[52:53] op_sel_hi:[1,0]
	v_pk_mul_f32 v[36:37], v[36:37], v[52:53] op_sel_hi:[1,0]
	v_pk_mul_f32 v[38:39], v[38:39], v[52:53] op_sel_hi:[1,0]
	v_pk_fma_f32 v[50:51], v[20:21], v[50:51], v[2:3]
	v_pk_fma_f32 v[48:49], v[22:23], v[48:49], v[0:1]
	v_pk_fma_f32 v[46:47], v[24:25], v[46:47], v[6:7]
	v_pk_fma_f32 v[44:45], v[26:27], v[44:45], v[4:5]
	v_pk_fma_f32 v[42:43], v[28:29], v[42:43], v[10:11]
	v_pk_fma_f32 v[40:41], v[30:31], v[40:41], v[8:9]
	v_pk_fma_f32 v[38:39], v[32:33], v[38:39], v[14:15]
	v_pk_fma_f32 v[36:37], v[34:35], v[36:37], v[12:13]
	v_lshl_add_u64 v[54:55], v[18:19], 0, s[34:35]
	v_cvt_pk_bf16_f32 v48, v48, v49
	v_cvt_pk_bf16_f32 v49, v50, v51
	v_cvt_pk_bf16_f32 v44, v44, v45
	v_cvt_pk_bf16_f32 v45, v46, v47
	v_cvt_pk_bf16_f32 v40, v40, v41
	v_cvt_pk_bf16_f32 v41, v42, v43
	v_cvt_pk_bf16_f32 v36, v36, v37
	v_cvt_pk_bf16_f32 v37, v38, v39
	flat_store_dwordx2 v[54:55], v[48:49]
	flat_store_dwordx2 v[54:55], v[44:45] offset:512
	flat_store_dwordx2 v[54:55], v[40:41] offset:1024
	flat_store_dwordx2 v[54:55], v[36:37] offset:1536
	s_cbranch_scc0 .LBB0_122

.LBB0_770:
	v_lshl_add_u64 v[16:17], v[40:41], 0, s[72:73]
	v_add_co_u32_e32 v56, vcc, s23, v16
	s_add_i32 s0, s60, s3
	s_nop 0
	v_addc_co_u32_e32 v57, vcc, 0, v17, vcc
	s_add_u32 s1, s34, s72
	s_addc_u32 s40, s35, s73
	s_add_i32 s52, s0, 0xffffc000
	s_lshl_b64 s[36:37], s[52:53], 11
	s_add_u32 s22, s44, s36
	s_addc_u32 s36, s45, s37
	s_cmpk_lt_i32 s0, 0x4000
	s_cselect_b32 s37, s40, s36
	s_cselect_b32 s36, s1, s22
	v_lshl_add_u64 v[60:61], s[36:37], 0, v[176:177]
	s_add_i32 s40, s0, 1
	s_ashr_i32 s41, s40, 31
	s_lshl_b64 s[36:37], s[40:41], 11
	v_lshl_add_u64 v[66:67], v[34:35], 0, s[36:37]
	s_add_u32 s1, s38, s36
	s_addc_u32 s40, s39, s37
	s_add_i32 s52, s0, 0xffffc001
	v_lshl_add_u64 v[44:45], v[38:39], 0, s[36:37]
	s_lshl_b64 s[36:37], s[52:53], 11
	s_add_u32 s22, s44, s36
	s_addc_u32 s36, s45, s37
	s_cmpk_lt_i32 s0, 0x3fff
	s_cselect_b32 s37, s40, s36
	s_cselect_b32 s36, s1, s22
	v_lshl_add_u64 v[64:65], s[36:37], 0, v[176:177]
	s_add_i32 s40, s0, 2
	s_ashr_i32 s41, s40, 31
	s_lshl_b64 s[36:37], s[40:41], 11
	s_add_u32 s1, s38, s36
	s_addc_u32 s40, s39, s37
	s_add_i32 s52, s0, 0xffffc002
	v_lshl_add_u64 v[54:55], v[34:35], 0, s[36:37]
	v_lshl_add_u64 v[46:47], v[38:39], 0, s[36:37]
	s_lshl_b64 s[36:37], s[52:53], 11
	s_add_u32 s22, s44, s36
	s_addc_u32 s36, s45, s37
	v_lshl_add_u64 v[42:43], v[36:37], 0, s[72:73]
	s_cmpk_lt_i32 s0, 0x3ffe
	v_add_co_u32_e32 v42, vcc, s49, v42
	s_cselect_b32 s37, s40, s36
	s_cselect_b32 s36, s1, s22
	s_add_i32 s40, s0, 3
	v_addc_co_u32_e32 v43, vcc, 0, v43, vcc
	s_ashr_i32 s41, s40, 31
	v_lshl_add_u64 v[52:53], s[36:37], 0, v[176:177]
	s_lshl_b64 s[36:37], s[40:41], 11
	s_add_u32 s40, s38, s36
	s_addc_u32 s1, s39, s37
	s_add_i32 s52, s0, 0xffffc003
	v_lshl_add_u64 v[50:51], v[34:35], 0, s[36:37]
	v_lshl_add_u64 v[16:17], v[38:39], 0, s[36:37]
	s_lshl_b64 s[36:37], s[52:53], 11
	s_add_u32 s22, s44, s36
	s_addc_u32 s36, s45, s37
	s_cmpk_lt_i32 s0, 0x3ffd
	s_cselect_b32 s1, s1, s36
	s_cselect_b32 s0, s40, s22
	v_lshl_add_u64 v[48:49], s[0:1], 0, v[176:177]
	s_add_i32 s3, s3, 4
	s_add_u32 s34, s34, 0x2000
	s_addc_u32 s35, s35, 0
	v_lshl_add_u64 v[36:37], v[36:37], 0, s[42:43]
	v_lshl_add_u64 v[40:41], v[40:41], 0, s[42:43]
	s_cmp_ge_i32 s3, s7
	global_load_dwordx2 v[120:121], v[56:57], off
	global_load_dwordx2 v[122:123], v[56:57], off offset:512
	global_load_dwordx2 v[124:125], v[56:57], off offset:1024
	global_load_dwordx2 v[126:127], v[56:57], off offset:1536
	global_load_dwordx2 v[128:129], v[66:67], off
	global_load_dwordx2 v[130:131], v[66:67], off offset:512
	global_load_dwordx2 v[132:133], v[66:67], off offset:1024
	global_load_dwordx2 v[134:135], v[66:67], off offset:1536
	global_load_dwordx2 v[136:137], v[54:55], off
	global_load_dwordx2 v[138:139], v[54:55], off offset:512
	global_load_dwordx2 v[140:141], v[54:55], off offset:1024
	global_load_dwordx2 v[142:143], v[54:55], off offset:1536
	global_load_dwordx2 v[144:145], v[50:51], off
	global_load_dwordx2 v[146:147], v[50:51], off offset:512
	global_load_dwordx2 v[148:149], v[50:51], off offset:1024
	global_load_dwordx2 v[150:151], v[50:51], off offset:1536
	s_waitcnt vmcnt(0)
	v_mov_b32_e32 v58, v120
	v_mov_b32_e32 v59, v121
	flat_store_dwordx2 v[60:61], v[58:59]
	v_mov_b32_e32 v62, v122
	v_mov_b32_e32 v63, v123
	v_cvt_f32_f16_sdwa v75, v58 dst_sel:DWORD dst_unused:UNUSED_PAD src0_sel:WORD_1
	v_cvt_f32_f16_sdwa v77, v59 dst_sel:DWORD dst_unused:UNUSED_PAD src0_sel:WORD_1
	v_cvt_f32_f16_e32 v74, v58
	v_cvt_f32_f16_e32 v76, v59
	v_mov_b32_e32 v80, v75
	v_mov_b32_e32 v81, v77
	v_mov_b32_e32 v58, v74
	v_mov_b32_e32 v59, v76
	v_pk_mul_f32 v[80:81], v[80:81], v[80:81]
	flat_store_dwordx2 v[60:61], v[62:63] offset:512
	v_mov_b32_e32 v78, v124
	v_mov_b32_e32 v79, v125
	v_pk_fma_f32 v[58:59], v[58:59], v[58:59], v[80:81]
	v_cvt_f32_f16_e32 v80, v62
	v_cvt_f32_f16_sdwa v81, v62 dst_sel:DWORD dst_unused:UNUSED_PAD src0_sel:WORD_1
	v_cvt_f32_f16_e32 v62, v63
	v_cvt_f32_f16_sdwa v63, v63 dst_sel:DWORD dst_unused:UNUSED_PAD src0_sel:WORD_1
	v_mov_b32_e32 v82, v80
	v_mov_b32_e32 v84, v81
	v_mov_b32_e32 v83, v62
	v_mov_b32_e32 v85, v63
	v_pk_mul_f32 v[84:85], v[84:85], v[84:85]
	v_pk_add_f32 v[58:59], v[58:59], v[58:59] op_sel:[0,1] op_sel_hi:[1,0]
	v_pk_fma_f32 v[82:83], v[82:83], v[82:83], v[84:85]
	flat_store_dwordx2 v[60:61], v[78:79] offset:1024
	v_mov_b32_e32 v56, v126
	v_mov_b32_e32 v57, v127
	v_cvt_f32_f16_sdwa v85, v78 dst_sel:DWORD dst_unused:UNUSED_PAD src0_sel:WORD_1
	v_cvt_f32_f16_sdwa v87, v79 dst_sel:DWORD dst_unused:UNUSED_PAD src0_sel:WORD_1
	v_cvt_f32_f16_e32 v84, v78
	v_cvt_f32_f16_e32 v86, v79
	v_mul_f32_e32 v78, v85, v85
	v_mul_f32_e32 v88, v87, v87
	v_pk_add_f32 v[82:83], v[82:83], v[82:83] op_sel:[0,1] op_sel_hi:[1,0]
	v_pk_fma_f32 v[78:79], v[84:85], v[84:85], v[78:79] op_sel_hi:[1,1,0]
	v_pk_fma_f32 v[88:89], v[86:87], v[86:87], v[88:89] op_sel_hi:[1,1,0]
	flat_store_dwordx2 v[60:61], v[56:57] offset:1536
	v_mov_b32_e32 v94, v128
	v_mov_b32_e32 v95, v129
	v_cvt_f32_f16_e32 v90, v56
	v_cvt_f32_f16_sdwa v91, v56 dst_sel:DWORD dst_unused:UNUSED_PAD src0_sel:WORD_1
	v_cvt_f32_f16_e32 v92, v57
	v_cvt_f32_f16_sdwa v93, v57 dst_sel:DWORD dst_unused:UNUSED_PAD src0_sel:WORD_1
	v_pk_mul_f32 v[56:57], v[90:91], v[90:91]
	s_nop 0
	v_mov_b32_e32 v59, v56
	v_pk_mul_f32 v[60:61], v[92:93], v[92:93]
	v_mov_b32_e32 v83, v57
	v_mov_b32_e32 v79, v60
	v_mov_b32_e32 v89, v61
	v_pk_add_f32 v[56:57], v[58:59], v[82:83]
	v_pk_add_f32 v[58:59], v[78:79], v[88:89]
	flat_store_dwordx2 v[64:65], v[94:95]
	v_mov_b32_e32 v78, v130
	v_mov_b32_e32 v79, v131
	v_pk_add_f32 v[56:57], v[56:57], v[58:59]
	flat_store_dwordx2 v[64:65], v[78:79] offset:512
	v_add_f32_e32 v56, v56, v57
	ds_bpermute_b32 v57, v68, v56
	s_waitcnt lgkmcnt(0)
	v_add_f32_e32 v56, v56, v57
	ds_bpermute_b32 v57, v69, v56
	s_waitcnt lgkmcnt(0)
	v_add_f32_e32 v56, v56, v57
	ds_bpermute_b32 v57, v70, v56
	s_waitcnt lgkmcnt(0)
	v_add_f32_e32 v56, v56, v57
	ds_bpermute_b32 v57, v71, v56
	s_waitcnt lgkmcnt(0)
	v_add_f32_e32 v56, v56, v57
	ds_bpermute_b32 v57, v72, v56
	s_waitcnt lgkmcnt(0)
	v_add_f32_e32 v56, v56, v57
	ds_bpermute_b32 v57, v73, v56
	s_waitcnt lgkmcnt(0)
	v_add_f32_e32 v56, v56, v57
	v_fmamk_f32 v56, v56, 0x3a800000, v228
	v_mul_f32_e32 v57, 0x4f800000, v56
	v_cmp_gt_f32_e32 vcc, s89, v56
	s_nop 1
	v_cndmask_b32_e32 v56, v56, v57, vcc
	v_sqrt_f32_e32 v57, v56
	s_nop 0
	v_add_u32_e32 v58, -1, v57
	v_add_u32_e32 v59, 1, v57
	v_fma_f32 v60, -v58, v57, v56
	v_fma_f32 v61, -v59, v57, v56
	v_cmp_ge_f32_e64 s[0:1], 0, v60
	s_nop 1
	v_cndmask_b32_e64 v57, v57, v58, s[0:1]
	v_cmp_lt_f32_e64 s[0:1], 0, v61
	s_nop 1
	v_cndmask_b32_e64 v57, v57, v59, s[0:1]
	v_mul_f32_e32 v58, 0x37800000, v57
	v_cndmask_b32_e32 v57, v57, v58, vcc
	v_cmp_class_f32_e32 vcc, v56, v229
	s_nop 1
	v_cndmask_b32_e32 v56, v57, v56, vcc
	v_div_scale_f32 v57, s[0:1], v56, v56, 1.0
	v_rcp_f32_e32 v59, v57
	v_div_scale_f32 v58, vcc, 1.0, v56, 1.0
	v_fma_f32 v60, -v57, v59, 1.0
	v_fmac_f32_e32 v59, v60, v59
	v_mul_f32_e32 v60, v58, v59
	v_fma_f32 v61, -v57, v60, v58
	v_fmac_f32_e32 v60, v61, v59
	v_fma_f32 v57, -v57, v60, v58
	v_div_fmas_f32 v57, v57, v59, v60
	v_div_fixup_f32 v56, v57, v56, 1.0
	v_pk_mul_f32 v[58:59], v[74:75], v[56:57] op_sel_hi:[1,0]
	v_pk_mul_f32 v[74:75], v[80:81], v[56:57] op_sel_hi:[1,0]
	v_pk_mul_f32 v[80:81], v[86:87], v[56:57] op_sel_hi:[1,0]
	v_mov_b32_e32 v86, v132
	v_mov_b32_e32 v87, v133
	v_pk_mul_f32 v[60:61], v[76:77], v[56:57] op_sel_hi:[1,0]
	v_pk_mul_f32 v[76:77], v[84:85], v[56:57] op_sel_hi:[1,0]
	v_pk_mul_f32 v[62:63], v[62:63], v[56:57] op_sel_hi:[1,0]
	v_pk_mul_f32 v[82:83], v[90:91], v[56:57] op_sel_hi:[1,0]
	v_pk_mul_f32 v[56:57], v[92:93], v[56:57] op_sel_hi:[1,0]
	v_pk_fma_f32 v[60:61], v[18:19], v[60:61], v[2:3]
	v_pk_fma_f32 v[58:59], v[20:21], v[58:59], v[0:1]
	v_pk_fma_f32 v[74:75], v[24:25], v[74:75], v[4:5]
	v_pk_fma_f32 v[76:77], v[28:29], v[76:77], v[8:9]
	v_pk_fma_f32 v[84:85], v[30:31], v[56:57], v[14:15]
	v_cvt_pk_bf16_f32 v56, v58, v59
	v_cvt_pk_bf16_f32 v57, v60, v61
	v_cvt_pk_bf16_f32 v58, v74, v75
	v_cvt_pk_bf16_f32 v60, v76, v77
	v_cvt_f32_f16_sdwa v75, v94 dst_sel:DWORD dst_unused:UNUSED_PAD src0_sel:WORD_1
	v_cvt_f32_f16_sdwa v77, v95 dst_sel:DWORD dst_unused:UNUSED_PAD src0_sel:WORD_1
	v_cvt_f32_f16_e32 v74, v94
	v_cvt_f32_f16_e32 v76, v95
	v_pk_fma_f32 v[62:63], v[22:23], v[62:63], v[6:7]
	v_pk_fma_f32 v[82:83], v[32:33], v[82:83], v[12:13]
	v_pk_fma_f32 v[80:81], v[26:27], v[80:81], v[10:11]
	v_cvt_pk_bf16_f32 v59, v62, v63
	v_cvt_pk_bf16_f32 v62, v82, v83
	v_mov_b32_e32 v82, v75
	v_mov_b32_e32 v83, v77
	v_cvt_pk_bf16_f32 v61, v80, v81
	v_mov_b32_e32 v80, v74
	v_mov_b32_e32 v81, v76
	v_pk_mul_f32 v[82:83], v[82:83], v[82:83]
	v_cvt_pk_bf16_f32 v63, v84, v85
	v_pk_fma_f32 v[80:81], v[80:81], v[80:81], v[82:83]
	v_cvt_f32_f16_sdwa v83, v78 dst_sel:DWORD dst_unused:UNUSED_PAD src0_sel:WORD_1
	v_cvt_f32_f16_sdwa v85, v79 dst_sel:DWORD dst_unused:UNUSED_PAD src0_sel:WORD_1
	v_cvt_f32_f16_e32 v82, v78
	v_cvt_f32_f16_e32 v84, v79
	v_mov_b32_e32 v88, v83
	v_mov_b32_e32 v89, v85
	v_mov_b32_e32 v78, v82
	v_mov_b32_e32 v79, v84
	v_pk_mul_f32 v[88:89], v[88:89], v[88:89]
	v_pk_add_f32 v[80:81], v[80:81], v[80:81] op_sel:[0,1] op_sel_hi:[1,0]
	v_pk_fma_f32 v[78:79], v[78:79], v[78:79], v[88:89]
	flat_store_dwordx2 v[64:65], v[86:87] offset:1024
	v_mov_b32_e32 v66, v134
	v_mov_b32_e32 v67, v135
	v_cvt_f32_f16_sdwa v89, v86 dst_sel:DWORD dst_unused:UNUSED_PAD src0_sel:WORD_1
	v_cvt_f32_f16_sdwa v91, v87 dst_sel:DWORD dst_unused:UNUSED_PAD src0_sel:WORD_1
	v_cvt_f32_f16_e32 v88, v86
	v_cvt_f32_f16_e32 v90, v87
	v_mul_f32_e32 v86, v89, v89
	v_mul_f32_e32 v92, v91, v91
	v_pk_add_f32 v[78:79], v[78:79], v[78:79] op_sel:[0,1] op_sel_hi:[1,0]
	v_pk_fma_f32 v[86:87], v[88:89], v[88:89], v[86:87] op_sel_hi:[1,1,0]
	v_pk_fma_f32 v[92:93], v[90:91], v[90:91], v[92:93] op_sel_hi:[1,1,0]
	flat_store_dwordx2 v[64:65], v[66:67] offset:1536
	v_mov_b32_e32 v64, v136
	v_mov_b32_e32 v65, v137
	v_cvt_f32_f16_e32 v94, v66
	v_cvt_f32_f16_sdwa v95, v66 dst_sel:DWORD dst_unused:UNUSED_PAD src0_sel:WORD_1
	v_cvt_f32_f16_e32 v96, v67
	v_cvt_f32_f16_sdwa v97, v67 dst_sel:DWORD dst_unused:UNUSED_PAD src0_sel:WORD_1
	v_pk_mul_f32 v[66:67], v[94:95], v[94:95]
	s_nop 0
	v_mov_b32_e32 v81, v66
	v_pk_mul_f32 v[98:99], v[96:97], v[96:97]
	v_mov_b32_e32 v79, v67
	v_mov_b32_e32 v87, v98
	v_mov_b32_e32 v93, v99
	v_pk_add_f32 v[66:67], v[80:81], v[78:79]
	v_pk_add_f32 v[78:79], v[86:87], v[92:93]
	flat_store_dwordx2 v[52:53], v[64:65]
	v_pk_add_f32 v[66:67], v[66:67], v[78:79]
	s_nop 0
	v_add_f32_e32 v66, v66, v67
	ds_bpermute_b32 v67, v68, v66
	s_waitcnt lgkmcnt(0)
	v_add_f32_e32 v66, v66, v67
	ds_bpermute_b32 v67, v69, v66
	s_waitcnt lgkmcnt(0)
	v_add_f32_e32 v66, v66, v67
	ds_bpermute_b32 v67, v70, v66
	s_waitcnt lgkmcnt(0)
	v_add_f32_e32 v66, v66, v67
	ds_bpermute_b32 v67, v71, v66
	s_waitcnt lgkmcnt(0)
	v_add_f32_e32 v66, v66, v67
	ds_bpermute_b32 v67, v72, v66
	s_waitcnt lgkmcnt(0)
	v_add_f32_e32 v66, v66, v67
	ds_bpermute_b32 v67, v73, v66
	s_waitcnt lgkmcnt(0)
	v_add_f32_e32 v66, v66, v67
	v_fmamk_f32 v66, v66, 0x3a800000, v228
	v_mul_f32_e32 v67, 0x4f800000, v66
	v_cmp_gt_f32_e32 vcc, s89, v66
	s_nop 1
	v_cndmask_b32_e32 v66, v66, v67, vcc
	v_sqrt_f32_e32 v67, v66
	s_nop 0
	v_add_u32_e32 v78, -1, v67
	v_add_u32_e32 v79, 1, v67
	v_fma_f32 v80, -v78, v67, v66
	v_fma_f32 v81, -v79, v67, v66
	v_cmp_ge_f32_e64 s[0:1], 0, v80
	s_nop 1
	v_cndmask_b32_e64 v67, v67, v78, s[0:1]
	v_cmp_lt_f32_e64 s[0:1], 0, v81
	s_nop 1
	v_cndmask_b32_e64 v67, v67, v79, s[0:1]
	v_mul_f32_e32 v78, 0x37800000, v67
	v_cndmask_b32_e32 v67, v67, v78, vcc
	v_cmp_class_f32_e32 vcc, v66, v229
	s_nop 1
	v_cndmask_b32_e32 v78, v67, v66, vcc
	v_mov_b32_e32 v66, v138
	v_mov_b32_e32 v67, v139
	v_div_scale_f32 v79, s[0:1], v78, v78, 1.0
	v_rcp_f32_e32 v81, v79
	v_div_scale_f32 v80, vcc, 1.0, v78, 1.0
	v_fma_f32 v86, -v79, v81, 1.0
	v_fmac_f32_e32 v81, v86, v81
	v_mul_f32_e32 v86, v80, v81
	v_fma_f32 v87, -v79, v86, v80
	v_fmac_f32_e32 v86, v87, v81
	v_fma_f32 v79, -v79, v86, v80
	v_div_fmas_f32 v79, v79, v81, v86
	v_div_fixup_f32 v78, v79, v78, 1.0
	v_pk_mul_f32 v[86:87], v[90:91], v[78:79] op_sel_hi:[1,0]
	v_pk_mul_f32 v[74:75], v[74:75], v[78:79] op_sel_hi:[1,0]
	v_pk_mul_f32 v[76:77], v[76:77], v[78:79] op_sel_hi:[1,0]
	v_pk_mul_f32 v[80:81], v[82:83], v[78:79] op_sel_hi:[1,0]
	v_pk_mul_f32 v[82:83], v[84:85], v[78:79] op_sel_hi:[1,0]
	v_pk_mul_f32 v[84:85], v[88:89], v[78:79] op_sel_hi:[1,0]
	v_pk_mul_f32 v[88:89], v[94:95], v[78:79] op_sel_hi:[1,0]
	v_pk_mul_f32 v[78:79], v[96:97], v[78:79] op_sel_hi:[1,0]
	v_pk_fma_f32 v[76:77], v[18:19], v[76:77], v[2:3]
	v_pk_fma_f32 v[74:75], v[20:21], v[74:75], v[0:1]
	v_pk_fma_f32 v[82:83], v[22:23], v[82:83], v[6:7]
	v_pk_fma_f32 v[80:81], v[24:25], v[80:81], v[4:5]
	v_pk_fma_f32 v[84:85], v[28:29], v[84:85], v[8:9]
	v_pk_fma_f32 v[78:79], v[30:31], v[78:79], v[14:15]
	v_cvt_pk_bf16_f32 v74, v74, v75
	v_cvt_pk_bf16_f32 v75, v76, v77
	v_cvt_pk_bf16_f32 v76, v80, v81
	v_cvt_pk_bf16_f32 v77, v82, v83
	v_cvt_pk_bf16_f32 v80, v84, v85
	v_cvt_pk_bf16_f32 v83, v78, v79
	v_cvt_f32_f16_sdwa v79, v64 dst_sel:DWORD dst_unused:UNUSED_PAD src0_sel:WORD_1
	v_cvt_f32_f16_sdwa v85, v65 dst_sel:DWORD dst_unused:UNUSED_PAD src0_sel:WORD_1
	v_cvt_f32_f16_e32 v78, v64
	v_cvt_f32_f16_e32 v84, v65
	v_pk_fma_f32 v[86:87], v[26:27], v[86:87], v[10:11]
	v_pk_fma_f32 v[88:89], v[32:33], v[88:89], v[12:13]
	v_cvt_pk_bf16_f32 v81, v86, v87
	v_mov_b32_e32 v86, v79
	v_mov_b32_e32 v87, v85
	v_mov_b32_e32 v64, v78
	v_mov_b32_e32 v65, v84
	v_pk_mul_f32 v[86:87], v[86:87], v[86:87]
	v_cvt_pk_bf16_f32 v82, v88, v89
	v_pk_fma_f32 v[64:65], v[64:65], v[64:65], v[86:87]
	flat_store_dwordx2 v[52:53], v[66:67] offset:512
	v_mov_b32_e32 v90, v140
	v_mov_b32_e32 v91, v141
	v_cvt_f32_f16_sdwa v87, v66 dst_sel:DWORD dst_unused:UNUSED_PAD src0_sel:WORD_1
	v_cvt_f32_f16_sdwa v89, v67 dst_sel:DWORD dst_unused:UNUSED_PAD src0_sel:WORD_1
	v_cvt_f32_f16_e32 v86, v66
	v_cvt_f32_f16_e32 v88, v67
	v_mov_b32_e32 v92, v87
	v_mov_b32_e32 v93, v89
	v_mov_b32_e32 v66, v86
	v_mov_b32_e32 v67, v88
	v_pk_mul_f32 v[92:93], v[92:93], v[92:93]
	v_pk_add_f32 v[64:65], v[64:65], v[64:65] op_sel:[0,1] op_sel_hi:[1,0]
	v_pk_fma_f32 v[66:67], v[66:67], v[66:67], v[92:93]
	flat_store_dwordx2 v[52:53], v[90:91] offset:1024
	v_mov_b32_e32 v54, v142
	v_mov_b32_e32 v55, v143
	v_cvt_f32_f16_sdwa v93, v90 dst_sel:DWORD dst_unused:UNUSED_PAD src0_sel:WORD_1
	v_cvt_f32_f16_sdwa v95, v91 dst_sel:DWORD dst_unused:UNUSED_PAD src0_sel:WORD_1
	v_cvt_f32_f16_e32 v92, v90
	v_cvt_f32_f16_e32 v94, v91
	v_mul_f32_e32 v90, v93, v93
	v_mul_f32_e32 v96, v95, v95
	v_pk_add_f32 v[66:67], v[66:67], v[66:67] op_sel:[0,1] op_sel_hi:[1,0]
	v_pk_fma_f32 v[90:91], v[92:93], v[92:93], v[90:91] op_sel_hi:[1,1,0]
	v_pk_fma_f32 v[96:97], v[94:95], v[94:95], v[96:97] op_sel_hi:[1,1,0]
	flat_store_dwordx2 v[52:53], v[54:55] offset:1536
	v_mov_b32_e32 v52, v144
	v_mov_b32_e32 v53, v145
	v_cvt_f32_f16_e32 v98, v54
	v_cvt_f32_f16_sdwa v99, v54 dst_sel:DWORD dst_unused:UNUSED_PAD src0_sel:WORD_1
	v_cvt_f32_f16_e32 v100, v55
	v_cvt_f32_f16_sdwa v101, v55 dst_sel:DWORD dst_unused:UNUSED_PAD src0_sel:WORD_1
	v_pk_mul_f32 v[54:55], v[98:99], v[98:99]
	s_nop 0
	v_mov_b32_e32 v65, v54
	v_pk_mul_f32 v[102:103], v[100:101], v[100:101]
	v_mov_b32_e32 v67, v55
	v_mov_b32_e32 v91, v102
	v_mov_b32_e32 v97, v103
	v_pk_add_f32 v[54:55], v[64:65], v[66:67]
	v_pk_add_f32 v[64:65], v[90:91], v[96:97]
	flat_store_dwordx2 v[48:49], v[52:53]
	v_pk_add_f32 v[54:55], v[54:55], v[64:65]
	s_nop 0
	v_add_f32_e32 v54, v54, v55
	ds_bpermute_b32 v55, v68, v54
	s_waitcnt lgkmcnt(0)
	v_add_f32_e32 v54, v54, v55
	ds_bpermute_b32 v55, v69, v54
	s_waitcnt lgkmcnt(0)
	v_add_f32_e32 v54, v54, v55
	ds_bpermute_b32 v55, v70, v54
	s_waitcnt lgkmcnt(0)
	v_add_f32_e32 v54, v54, v55
	ds_bpermute_b32 v55, v71, v54
	s_waitcnt lgkmcnt(0)
	v_add_f32_e32 v54, v54, v55
	ds_bpermute_b32 v55, v72, v54
	s_waitcnt lgkmcnt(0)
	v_add_f32_e32 v54, v54, v55
	ds_bpermute_b32 v55, v73, v54
	s_waitcnt lgkmcnt(0)
	v_add_f32_e32 v54, v54, v55
	v_fmamk_f32 v54, v54, 0x3a800000, v228
	v_mul_f32_e32 v55, 0x4f800000, v54
	v_cmp_gt_f32_e32 vcc, s89, v54
	s_nop 1
	v_cndmask_b32_e32 v64, v54, v55, vcc
	v_mov_b32_e32 v54, v146
	v_mov_b32_e32 v55, v147
	v_sqrt_f32_e32 v65, v64
	flat_store_dwordx2 v[48:49], v[54:55] offset:512
	v_add_u32_e32 v66, -1, v65
	v_add_u32_e32 v67, 1, v65
	v_fma_f32 v90, -v66, v65, v64
	v_fma_f32 v91, -v67, v65, v64
	v_cmp_ge_f32_e64 s[0:1], 0, v90
	s_nop 1
	v_cndmask_b32_e64 v65, v65, v66, s[0:1]
	v_cmp_lt_f32_e64 s[0:1], 0, v91
	s_nop 1
	v_cndmask_b32_e64 v65, v65, v67, s[0:1]
	v_mul_f32_e32 v66, 0x37800000, v65
	v_cndmask_b32_e32 v65, v65, v66, vcc
	v_cmp_class_f32_e32 vcc, v64, v229
	s_nop 1
	v_cndmask_b32_e32 v64, v65, v64, vcc
	v_div_scale_f32 v65, s[0:1], v64, v64, 1.0
	v_rcp_f32_e32 v67, v65
	v_div_scale_f32 v66, vcc, 1.0, v64, 1.0
	v_fma_f32 v90, -v65, v67, 1.0
	v_fmac_f32_e32 v67, v90, v67
	v_mul_f32_e32 v90, v66, v67
	v_fma_f32 v91, -v65, v90, v66
	v_fmac_f32_e32 v90, v91, v67
	v_fma_f32 v65, -v65, v90, v66
	v_div_fmas_f32 v65, v65, v67, v90
	v_mov_b32_e32 v66, v148
	v_mov_b32_e32 v67, v149
	v_div_fixup_f32 v64, v65, v64, 1.0
	v_pk_mul_f32 v[78:79], v[78:79], v[64:65] op_sel_hi:[1,0]
	v_pk_mul_f32 v[84:85], v[84:85], v[64:65] op_sel_hi:[1,0]
	v_pk_mul_f32 v[86:87], v[86:87], v[64:65] op_sel_hi:[1,0]
	v_pk_mul_f32 v[88:89], v[88:89], v[64:65] op_sel_hi:[1,0]
	v_pk_mul_f32 v[90:91], v[92:93], v[64:65] op_sel_hi:[1,0]
	v_pk_mul_f32 v[92:93], v[94:95], v[64:65] op_sel_hi:[1,0]
	v_pk_mul_f32 v[94:95], v[98:99], v[64:65] op_sel_hi:[1,0]
	v_pk_mul_f32 v[64:65], v[100:101], v[64:65] op_sel_hi:[1,0]
	v_pk_fma_f32 v[84:85], v[18:19], v[84:85], v[2:3]
	v_pk_fma_f32 v[78:79], v[20:21], v[78:79], v[0:1]
	v_pk_fma_f32 v[88:89], v[22:23], v[88:89], v[6:7]
	v_pk_fma_f32 v[64:65], v[30:31], v[64:65], v[14:15]
	v_cvt_pk_bf16_f32 v78, v78, v79
	v_cvt_pk_bf16_f32 v79, v84, v85
	v_cvt_pk_bf16_f32 v85, v88, v89
	v_cvt_pk_bf16_f32 v89, v64, v65
	v_cvt_f32_f16_e32 v64, v52
	v_cvt_f32_f16_sdwa v65, v52 dst_sel:DWORD dst_unused:UNUSED_PAD src0_sel:WORD_1
	v_cvt_f32_f16_e32 v52, v53
	v_cvt_f32_f16_sdwa v53, v53 dst_sel:DWORD dst_unused:UNUSED_PAD src0_sel:WORD_1
	v_pk_fma_f32 v[86:87], v[24:25], v[86:87], v[4:5]
	v_pk_fma_f32 v[92:93], v[26:27], v[92:93], v[10:11]
	v_pk_fma_f32 v[90:91], v[28:29], v[90:91], v[8:9]
	v_cvt_pk_bf16_f32 v84, v86, v87
	v_cvt_pk_bf16_f32 v87, v92, v93
	v_mov_b32_e32 v92, v65
	v_mov_b32_e32 v93, v53
	v_pk_fma_f32 v[94:95], v[32:33], v[94:95], v[12:13]
	v_cvt_pk_bf16_f32 v86, v90, v91
	v_mov_b32_e32 v90, v64
	v_mov_b32_e32 v91, v52
	v_pk_mul_f32 v[92:93], v[92:93], v[92:93]
	v_cvt_pk_bf16_f32 v88, v94, v95
	v_pk_fma_f32 v[90:91], v[90:91], v[90:91], v[92:93]
	v_cvt_f32_f16_sdwa v93, v54 dst_sel:DWORD dst_unused:UNUSED_PAD src0_sel:WORD_1
	v_cvt_f32_f16_sdwa v95, v55 dst_sel:DWORD dst_unused:UNUSED_PAD src0_sel:WORD_1
	v_cvt_f32_f16_e32 v92, v54
	v_cvt_f32_f16_e32 v94, v55
	v_mov_b32_e32 v96, v93
	v_mov_b32_e32 v97, v95
	v_mov_b32_e32 v54, v92
	v_mov_b32_e32 v55, v94
	v_pk_mul_f32 v[96:97], v[96:97], v[96:97]
	v_pk_add_f32 v[90:91], v[90:91], v[90:91] op_sel:[0,1] op_sel_hi:[1,0]
	v_pk_fma_f32 v[54:55], v[54:55], v[54:55], v[96:97]
	flat_store_dwordx2 v[48:49], v[66:67] offset:1024
	v_mov_b32_e32 v50, v150
	v_mov_b32_e32 v51, v151
	v_cvt_f32_f16_sdwa v97, v66 dst_sel:DWORD dst_unused:UNUSED_PAD src0_sel:WORD_1
	v_cvt_f32_f16_sdwa v99, v67 dst_sel:DWORD dst_unused:UNUSED_PAD src0_sel:WORD_1
	v_cvt_f32_f16_e32 v96, v66
	v_cvt_f32_f16_e32 v98, v67
	v_mul_f32_e32 v66, v97, v97
	v_mul_f32_e32 v100, v99, v99
	v_pk_add_f32 v[54:55], v[54:55], v[54:55] op_sel:[0,1] op_sel_hi:[1,0]
	v_pk_fma_f32 v[66:67], v[96:97], v[96:97], v[66:67] op_sel_hi:[1,1,0]
	v_pk_fma_f32 v[100:101], v[98:99], v[98:99], v[100:101] op_sel_hi:[1,1,0]
	flat_store_dwordx2 v[48:49], v[50:51] offset:1536
	flat_store_dwordx2 v[42:43], v[56:57]
	flat_store_dwordx2 v[42:43], v[58:59] offset:512
	flat_store_dwordx2 v[42:43], v[60:61] offset:1024
	flat_store_dwordx2 v[42:43], v[62:63] offset:1536
	flat_store_dwordx2 v[44:45], v[74:75]
	flat_store_dwordx2 v[44:45], v[76:77] offset:512
	flat_store_dwordx2 v[44:45], v[80:81] offset:1024
	flat_store_dwordx2 v[44:45], v[82:83] offset:1536
	flat_store_dwordx2 v[46:47], v[78:79]
	flat_store_dwordx2 v[46:47], v[84:85] offset:512
	flat_store_dwordx2 v[46:47], v[86:87] offset:1024
	flat_store_dwordx2 v[46:47], v[88:89] offset:1536
	v_cvt_f32_f16_e32 v102, v50
	v_cvt_f32_f16_sdwa v103, v50 dst_sel:DWORD dst_unused:UNUSED_PAD src0_sel:WORD_1
	v_cvt_f32_f16_e32 v104, v51
	v_cvt_f32_f16_sdwa v105, v51 dst_sel:DWORD dst_unused:UNUSED_PAD src0_sel:WORD_1
	v_pk_mul_f32 v[42:43], v[102:103], v[102:103]
	s_nop 0
	v_mov_b32_e32 v91, v42
	v_pk_mul_f32 v[44:45], v[104:105], v[104:105]
	v_mov_b32_e32 v55, v43
	v_mov_b32_e32 v67, v44
	v_mov_b32_e32 v101, v45
	v_pk_add_f32 v[42:43], v[90:91], v[54:55]
	v_pk_add_f32 v[44:45], v[66:67], v[100:101]
	s_nop 0
	v_pk_add_f32 v[42:43], v[42:43], v[44:45]
	s_nop 0
	v_add_f32_e32 v42, v42, v43
	ds_bpermute_b32 v43, v68, v42
	s_waitcnt lgkmcnt(0)
	v_add_f32_e32 v42, v42, v43
	ds_bpermute_b32 v43, v69, v42
	s_waitcnt lgkmcnt(0)
	v_add_f32_e32 v42, v42, v43
	ds_bpermute_b32 v43, v70, v42
	s_waitcnt lgkmcnt(0)
	v_add_f32_e32 v42, v42, v43
	ds_bpermute_b32 v43, v71, v42
	s_waitcnt lgkmcnt(0)
	v_add_f32_e32 v42, v42, v43
	ds_bpermute_b32 v43, v72, v42
	s_waitcnt lgkmcnt(0)
	v_add_f32_e32 v42, v42, v43
	ds_bpermute_b32 v43, v73, v42
	s_waitcnt lgkmcnt(0)
	v_add_f32_e32 v42, v42, v43
	v_fmamk_f32 v42, v42, 0x3a800000, v228
	v_mul_f32_e32 v43, 0x4f800000, v42
	v_cmp_gt_f32_e32 vcc, s89, v42
	s_nop 1
	v_cndmask_b32_e32 v42, v42, v43, vcc
	v_sqrt_f32_e32 v43, v42
	s_nop 0
	v_add_u32_e32 v44, -1, v43
	v_add_u32_e32 v45, 1, v43
	v_fma_f32 v46, -v44, v43, v42
	v_fma_f32 v47, -v45, v43, v42
	v_cmp_ge_f32_e64 s[0:1], 0, v46
	s_nop 1
	v_cndmask_b32_e64 v43, v43, v44, s[0:1]
	v_cmp_lt_f32_e64 s[0:1], 0, v47
	s_nop 1
	v_cndmask_b32_e64 v43, v43, v45, s[0:1]
	v_mul_f32_e32 v44, 0x37800000, v43
	v_cndmask_b32_e32 v43, v43, v44, vcc
	v_cmp_class_f32_e32 vcc, v42, v229
	s_nop 1
	v_cndmask_b32_e32 v42, v43, v42, vcc
	v_div_scale_f32 v43, s[0:1], v42, v42, 1.0
	v_rcp_f32_e32 v45, v43
	v_div_scale_f32 v44, vcc, 1.0, v42, 1.0
	v_fma_f32 v46, -v43, v45, 1.0
	v_fmac_f32_e32 v45, v46, v45
	v_mul_f32_e32 v46, v44, v45
	v_fma_f32 v47, -v43, v46, v44
	v_fmac_f32_e32 v46, v47, v45
	v_fma_f32 v43, -v43, v46, v44
	v_div_fmas_f32 v43, v43, v45, v46
	v_div_fixup_f32 v42, v43, v42, 1.0
	v_pk_mul_f32 v[44:45], v[64:65], v[42:43] op_sel_hi:[1,0]
	v_pk_mul_f32 v[46:47], v[52:53], v[42:43] op_sel_hi:[1,0]
	v_pk_mul_f32 v[48:49], v[92:93], v[42:43] op_sel_hi:[1,0]
	v_pk_mul_f32 v[50:51], v[94:95], v[42:43] op_sel_hi:[1,0]
	v_pk_mul_f32 v[52:53], v[96:97], v[42:43] op_sel_hi:[1,0]
	v_pk_mul_f32 v[54:55], v[98:99], v[42:43] op_sel_hi:[1,0]
	v_pk_mul_f32 v[56:57], v[102:103], v[42:43] op_sel_hi:[1,0]
	v_pk_mul_f32 v[42:43], v[104:105], v[42:43] op_sel_hi:[1,0]
	v_pk_fma_f32 v[46:47], v[18:19], v[46:47], v[2:3]
	v_pk_fma_f32 v[44:45], v[20:21], v[44:45], v[0:1]
	v_pk_fma_f32 v[50:51], v[22:23], v[50:51], v[6:7]
	v_pk_fma_f32 v[48:49], v[24:25], v[48:49], v[4:5]
	v_pk_fma_f32 v[54:55], v[26:27], v[54:55], v[10:11]
	v_pk_fma_f32 v[52:53], v[28:29], v[52:53], v[8:9]
	v_pk_fma_f32 v[42:43], v[30:31], v[42:43], v[14:15]
	v_pk_fma_f32 v[56:57], v[32:33], v[56:57], v[12:13]
	v_cvt_pk_bf16_f32 v44, v44, v45
	v_cvt_pk_bf16_f32 v45, v46, v47
	v_cvt_pk_bf16_f32 v46, v48, v49
	v_cvt_pk_bf16_f32 v47, v50, v51
	v_cvt_pk_bf16_f32 v48, v52, v53
	v_cvt_pk_bf16_f32 v49, v54, v55
	v_cvt_pk_bf16_f32 v50, v56, v57
	v_cvt_pk_bf16_f32 v51, v42, v43
	flat_store_dwordx2 v[16:17], v[44:45]
	flat_store_dwordx2 v[16:17], v[46:47] offset:512
	flat_store_dwordx2 v[16:17], v[48:49] offset:1024
	flat_store_dwordx2 v[16:17], v[50:51] offset:1536
	s_cbranch_scc0 .LBB0_770

.LBB0_789:
	v_lshl_add_u64 v[36:37], s[40:41], 0, v[176:177]
	v_add_co_u32_e32 v36, vcc, 0x4000000, v36
	s_add_i32 s3, s8, s22
	s_nop 0
	v_addc_co_u32_e32 v37, vcc, 0, v37, vcc
	s_add_i32 s0, s3, 1
	s_ashr_i32 s1, s0, 31
	s_lshl_b64 s[42:43], s[0:1], 11
	s_add_i32 s0, s3, 2
	s_ashr_i32 s1, s0, 31
	s_lshl_b64 s[36:37], s[0:1], 11
	s_add_i32 s0, s3, 3
	s_ashr_i32 s1, s0, 31
	s_lshl_b64 s[34:35], s[0:1], 11
	s_add_i32 s22, s22, 4
	s_add_u32 s40, s40, 0x2000
	s_addc_u32 s41, s41, 0
	v_lshl_add_u64 v[152:153], v[32:33], 0, s[42:43]
	v_lshl_add_u64 v[154:155], v[32:33], 0, s[36:37]
	v_lshl_add_u64 v[156:157], v[32:33], 0, s[34:35]
	global_load_dwordx2 v[120:121], v[36:37], off
	global_load_dwordx2 v[122:123], v[36:37], off offset:512
	global_load_dwordx2 v[124:125], v[36:37], off offset:1024
	global_load_dwordx2 v[126:127], v[36:37], off offset:1536
	global_load_dwordx2 v[128:129], v[152:153], off
	global_load_dwordx2 v[130:131], v[152:153], off offset:512
	global_load_dwordx2 v[132:133], v[152:153], off offset:1024
	global_load_dwordx2 v[134:135], v[152:153], off offset:1536
	global_load_dwordx2 v[136:137], v[154:155], off
	global_load_dwordx2 v[138:139], v[154:155], off offset:512
	global_load_dwordx2 v[140:141], v[154:155], off offset:1024
	global_load_dwordx2 v[142:143], v[154:155], off offset:1536
	global_load_dwordx2 v[144:145], v[156:157], off
	global_load_dwordx2 v[146:147], v[156:157], off offset:512
	global_load_dwordx2 v[148:149], v[156:157], off offset:1024
	global_load_dwordx2 v[150:151], v[156:157], off offset:1536
	s_waitcnt vmcnt(0)
	v_mov_b32_e32 v38, v120
	v_mov_b32_e32 v39, v121
	v_cvt_f32_f16_e32 v80, v38
	v_cvt_f32_f16_sdwa v81, v38 dst_sel:DWORD dst_unused:UNUSED_PAD src0_sel:WORD_1
	v_cvt_f32_f16_e32 v82, v39
	v_cvt_f32_f16_sdwa v83, v39 dst_sel:DWORD dst_unused:UNUSED_PAD src0_sel:WORD_1
	v_mov_b32_e32 v38, v122
	v_mov_b32_e32 v39, v123
	v_mov_b32_e32 v110, v81
	v_mov_b32_e32 v108, v80
	v_mov_b32_e32 v111, v83
	v_mov_b32_e32 v109, v82
	v_pk_mul_f32 v[110:111], v[110:111], v[110:111]
	v_cvt_f32_f16_e32 v76, v38
	v_cvt_f32_f16_sdwa v77, v38 dst_sel:DWORD dst_unused:UNUSED_PAD src0_sel:WORD_1
	v_cvt_f32_f16_e32 v78, v39
	v_cvt_f32_f16_sdwa v79, v39 dst_sel:DWORD dst_unused:UNUSED_PAD src0_sel:WORD_1
	v_mov_b32_e32 v38, v124
	v_mov_b32_e32 v39, v125
	v_mov_b32_e32 v112, v77
	v_mov_b32_e32 v36, v126
	v_mov_b32_e32 v37, v127
	v_mov_b32_e32 v113, v79
	v_pk_fma_f32 v[108:109], v[108:109], v[108:109], v[110:111]
	v_mov_b32_e32 v110, v76
	v_mov_b32_e32 v111, v78
	v_pk_mul_f32 v[112:113], v[112:113], v[112:113]
	v_pk_add_f32 v[108:109], v[108:109], v[108:109] op_sel:[0,1] op_sel_hi:[1,0]
	v_pk_fma_f32 v[110:111], v[110:111], v[110:111], v[112:113]
	v_cvt_f32_f16_e32 v72, v38
	v_cvt_f32_f16_sdwa v73, v38 dst_sel:DWORD dst_unused:UNUSED_PAD src0_sel:WORD_1
	v_cvt_f32_f16_e32 v68, v36
	v_cvt_f32_f16_sdwa v69, v36 dst_sel:DWORD dst_unused:UNUSED_PAD src0_sel:WORD_1
	v_cvt_f32_f16_e32 v70, v37
	v_cvt_f32_f16_sdwa v71, v37 dst_sel:DWORD dst_unused:UNUSED_PAD src0_sel:WORD_1
	v_lshl_add_u64 v[36:37], v[32:33], 0, s[42:43]
	v_cvt_f32_f16_e32 v74, v39
	v_cvt_f32_f16_sdwa v75, v39 dst_sel:DWORD dst_unused:UNUSED_PAD src0_sel:WORD_1
	v_mov_b32_e32 v38, v128
	v_mov_b32_e32 v39, v129
	v_mul_f32_e32 v100, v73, v73
	v_pk_fma_f32 v[112:113], v[72:73], v[72:73], v[100:101] op_sel_hi:[1,1,0]
	v_mul_f32_e32 v100, v75, v75
	v_pk_add_f32 v[110:111], v[110:111], v[110:111] op_sel:[0,1] op_sel_hi:[1,0]
	v_pk_fma_f32 v[114:115], v[74:75], v[74:75], v[100:101] op_sel_hi:[1,1,0]
	v_pk_mul_f32 v[116:117], v[68:69], v[68:69]
	v_pk_mul_f32 v[118:119], v[70:71], v[70:71]
	v_mov_b32_e32 v109, v116
	v_mov_b32_e32 v111, v117
	v_mov_b32_e32 v113, v118
	v_mov_b32_e32 v115, v119
	v_pk_add_f32 v[108:109], v[108:109], v[110:111]
	v_pk_add_f32 v[110:111], v[112:113], v[114:115]
	v_cvt_f32_f16_e32 v96, v38
	v_cvt_f32_f16_sdwa v97, v38 dst_sel:DWORD dst_unused:UNUSED_PAD src0_sel:WORD_1
	v_cvt_f32_f16_e32 v98, v39
	v_cvt_f32_f16_sdwa v99, v39 dst_sel:DWORD dst_unused:UNUSED_PAD src0_sel:WORD_1
	v_mov_b32_e32 v38, v130
	v_mov_b32_e32 v39, v131
	v_pk_add_f32 v[108:109], v[108:109], v[110:111]
	v_cvt_f32_f16_e32 v92, v38
	v_cvt_f32_f16_sdwa v93, v38 dst_sel:DWORD dst_unused:UNUSED_PAD src0_sel:WORD_1
	v_cvt_f32_f16_e32 v94, v39
	v_cvt_f32_f16_sdwa v95, v39 dst_sel:DWORD dst_unused:UNUSED_PAD src0_sel:WORD_1
	v_mov_b32_e32 v38, v132
	v_mov_b32_e32 v39, v133
	v_add_f32_e32 v100, v108, v109
	v_mov_b32_e32 v36, v134
	v_mov_b32_e32 v37, v135
	ds_bpermute_b32 v107, v101, v100
	s_waitcnt lgkmcnt(0)
	v_add_f32_e32 v100, v100, v107
	ds_bpermute_b32 v107, v102, v100
	s_waitcnt lgkmcnt(0)
	v_add_f32_e32 v100, v100, v107
	ds_bpermute_b32 v107, v103, v100
	s_waitcnt lgkmcnt(0)
	v_add_f32_e32 v100, v100, v107
	ds_bpermute_b32 v107, v104, v100
	s_waitcnt lgkmcnt(0)
	v_add_f32_e32 v100, v100, v107
	ds_bpermute_b32 v107, v105, v100
	s_waitcnt lgkmcnt(0)
	v_add_f32_e32 v100, v100, v107
	ds_bpermute_b32 v107, v106, v100
	s_waitcnt lgkmcnt(0)
	v_add_f32_e32 v100, v100, v107
	v_fmamk_f32 v100, v100, 0x3a800000, v228
	v_cmp_gt_f32_e32 vcc, s89, v100
	v_mul_f32_e32 v107, 0x4f800000, v100
	v_cvt_f32_f16_e32 v88, v38
	v_cvt_f32_f16_sdwa v89, v38 dst_sel:DWORD dst_unused:UNUSED_PAD src0_sel:WORD_1
	v_cvt_f32_f16_e32 v84, v36
	v_cvt_f32_f16_sdwa v85, v36 dst_sel:DWORD dst_unused:UNUSED_PAD src0_sel:WORD_1
	v_cvt_f32_f16_e32 v86, v37
	v_cvt_f32_f16_sdwa v87, v37 dst_sel:DWORD dst_unused:UNUSED_PAD src0_sel:WORD_1
	v_lshl_add_u64 v[36:37], v[32:33], 0, s[36:37]
	v_cvt_f32_f16_e32 v90, v39
	v_cvt_f32_f16_sdwa v91, v39 dst_sel:DWORD dst_unused:UNUSED_PAD src0_sel:WORD_1
	v_mov_b32_e32 v38, v136
	v_mov_b32_e32 v39, v137
	v_cndmask_b32_e32 v100, v100, v107, vcc
	v_sqrt_f32_e32 v107, v100
	v_cvt_f32_f16_e32 v64, v38
	v_cvt_f32_f16_sdwa v65, v38 dst_sel:DWORD dst_unused:UNUSED_PAD src0_sel:WORD_1
	v_cvt_f32_f16_e32 v66, v39
	v_cvt_f32_f16_sdwa v67, v39 dst_sel:DWORD dst_unused:UNUSED_PAD src0_sel:WORD_1
	v_mov_b32_e32 v38, v138
	v_mov_b32_e32 v39, v139
	v_add_u32_e32 v108, -1, v107
	v_fma_f32 v109, -v108, v107, v100
	v_cmp_ge_f32_e64 s[0:1], 0, v109
	v_add_u32_e32 v109, 1, v107
	v_cvt_f32_f16_e32 v60, v38
	v_cvt_f32_f16_sdwa v61, v38 dst_sel:DWORD dst_unused:UNUSED_PAD src0_sel:WORD_1
	v_cvt_f32_f16_e32 v62, v39
	v_cvt_f32_f16_sdwa v63, v39 dst_sel:DWORD dst_unused:UNUSED_PAD src0_sel:WORD_1
	v_mov_b32_e32 v38, v140
	v_mov_b32_e32 v39, v141
	v_cndmask_b32_e64 v108, v107, v108, s[0:1]
	v_mov_b32_e32 v36, v142
	v_mov_b32_e32 v37, v143
	v_fma_f32 v107, -v109, v107, v100
	v_cmp_lt_f32_e64 s[0:1], 0, v107
	v_cvt_f32_f16_e32 v56, v38
	v_cvt_f32_f16_sdwa v57, v38 dst_sel:DWORD dst_unused:UNUSED_PAD src0_sel:WORD_1
	v_cvt_f32_f16_e32 v52, v36
	v_cvt_f32_f16_sdwa v53, v36 dst_sel:DWORD dst_unused:UNUSED_PAD src0_sel:WORD_1
	v_cvt_f32_f16_e32 v54, v37
	v_cvt_f32_f16_sdwa v55, v37 dst_sel:DWORD dst_unused:UNUSED_PAD src0_sel:WORD_1
	v_lshl_add_u64 v[36:37], v[32:33], 0, s[34:35]
	v_cvt_f32_f16_e32 v58, v39
	v_cvt_f32_f16_sdwa v59, v39 dst_sel:DWORD dst_unused:UNUSED_PAD src0_sel:WORD_1
	v_mov_b32_e32 v38, v144
	v_mov_b32_e32 v39, v145
	v_cndmask_b32_e64 v107, v108, v109, s[0:1]
	v_mul_f32_e32 v108, 0x37800000, v107
	v_cndmask_b32_e32 v107, v107, v108, vcc
	v_cmp_class_f32_e32 vcc, v100, v229
	v_cvt_f32_f16_e32 v48, v38
	v_cvt_f32_f16_sdwa v49, v38 dst_sel:DWORD dst_unused:UNUSED_PAD src0_sel:WORD_1
	v_cvt_f32_f16_e32 v50, v39
	v_cvt_f32_f16_sdwa v51, v39 dst_sel:DWORD dst_unused:UNUSED_PAD src0_sel:WORD_1
	v_mov_b32_e32 v38, v146
	v_mov_b32_e32 v39, v147
	v_cndmask_b32_e32 v100, v107, v100, vcc
	v_div_scale_f32 v107, s[0:1], v100, v100, 1.0
	v_rcp_f32_e32 v108, v107
	v_cvt_f32_f16_e32 v44, v38
	v_cvt_f32_f16_sdwa v45, v38 dst_sel:DWORD dst_unused:UNUSED_PAD src0_sel:WORD_1
	v_cvt_f32_f16_e32 v46, v39
	v_cvt_f32_f16_sdwa v47, v39 dst_sel:DWORD dst_unused:UNUSED_PAD src0_sel:WORD_1
	v_mov_b32_e32 v38, v148
	v_mov_b32_e32 v39, v149
	v_fma_f32 v109, -v107, v108, 1.0
	v_fmac_f32_e32 v108, v109, v108
	v_div_scale_f32 v109, vcc, 1.0, v100, 1.0
	v_mul_f32_e32 v110, v109, v108
	v_fma_f32 v111, -v107, v110, v109
	v_fmac_f32_e32 v110, v111, v108
	v_fma_f32 v107, -v107, v110, v109
	v_div_fmas_f32 v107, v107, v108, v110
	v_div_fixup_f32 v100, v107, v100, 1.0
	v_pk_mul_f32 v[80:81], v[80:81], v[100:101] op_sel_hi:[1,0]
	v_pk_mul_f32 v[82:83], v[82:83], v[100:101] op_sel_hi:[1,0]
	v_lshl_add_u64 v[108:109], s[38:39], 0, v[176:177]
	v_pk_fma_f32 v[82:83], v[16:17], v[82:83], v[2:3]
	v_pk_fma_f32 v[80:81], v[18:19], v[80:81], v[0:1]
	v_pk_mul_f32 v[72:73], v[72:73], v[100:101] op_sel_hi:[1,0]
	v_pk_mul_f32 v[74:75], v[74:75], v[100:101] op_sel_hi:[1,0]
	v_pk_mul_f32 v[68:69], v[68:69], v[100:101] op_sel_hi:[1,0]
	v_pk_mul_f32 v[70:71], v[70:71], v[100:101] op_sel_hi:[1,0]
	v_cvt_pk_bf16_f32 v80, v80, v81
	v_cvt_pk_bf16_f32 v81, v82, v83
	v_add_co_u32_e32 v82, vcc, s49, v108
	v_pk_fma_f32 v[74:75], v[24:25], v[74:75], v[10:11]
	v_pk_fma_f32 v[72:73], v[26:27], v[72:73], v[8:9]
	v_pk_fma_f32 v[70:71], v[28:29], v[70:71], v[14:15]
	v_pk_fma_f32 v[68:69], v[30:31], v[68:69], v[12:13]
	v_addc_co_u32_e32 v83, vcc, 0, v109, vcc
	v_cvt_pk_bf16_f32 v72, v72, v73
	v_cvt_pk_bf16_f32 v73, v74, v75
	v_cvt_pk_bf16_f32 v68, v68, v69
	v_cvt_pk_bf16_f32 v69, v70, v71
	v_mov_b32_e32 v70, v97
	v_mov_b32_e32 v71, v99
	v_pk_mul_f32 v[76:77], v[76:77], v[100:101] op_sel_hi:[1,0]
	v_pk_mul_f32 v[78:79], v[78:79], v[100:101] op_sel_hi:[1,0]
	v_pk_mul_f32 v[70:71], v[70:71], v[70:71]
	v_pk_fma_f32 v[78:79], v[20:21], v[78:79], v[6:7]
	v_pk_fma_f32 v[76:77], v[22:23], v[76:77], v[4:5]
	v_mul_f32_e32 v74, v91, v91
	v_cvt_pk_bf16_f32 v76, v76, v77
	v_cvt_pk_bf16_f32 v77, v78, v79
	v_pk_fma_f32 v[74:75], v[90:91], v[90:91], v[74:75] op_sel_hi:[1,1,0]
	v_pk_mul_f32 v[78:79], v[86:87], v[86:87]
	s_add_u32 s38, s38, 0x2000
	v_mov_b32_e32 v75, v79
	s_addc_u32 s39, s39, 0
	s_cmp_ge_i32 s22, s7
	v_cvt_f32_f16_e32 v40, v38
	v_cvt_f32_f16_sdwa v41, v38 dst_sel:DWORD dst_unused:UNUSED_PAD src0_sel:WORD_1
	v_cvt_f32_f16_e32 v42, v39
	v_cvt_f32_f16_sdwa v43, v39 dst_sel:DWORD dst_unused:UNUSED_PAD src0_sel:WORD_1
	v_mov_b32_e32 v38, v150
	v_mov_b32_e32 v39, v151
	v_cvt_f32_f16_e32 v36, v38
	flat_store_dwordx2 v[82:83], v[72:73] offset:1024
	flat_store_dwordx2 v[82:83], v[68:69] offset:1536
	v_mov_b32_e32 v68, v96
	v_mov_b32_e32 v69, v98
	v_mov_b32_e32 v72, v93
	v_mov_b32_e32 v73, v95
	v_pk_fma_f32 v[68:69], v[68:69], v[68:69], v[70:71]
	v_mov_b32_e32 v70, v92
	v_mov_b32_e32 v71, v94
	v_pk_mul_f32 v[72:73], v[72:73], v[72:73]
	flat_store_dwordx2 v[82:83], v[76:77] offset:512
	v_pk_fma_f32 v[70:71], v[70:71], v[70:71], v[72:73]
	v_mul_f32_e32 v72, v89, v89
	v_pk_add_f32 v[68:69], v[68:69], v[68:69] op_sel:[0,1] op_sel_hi:[1,0]
	v_pk_add_f32 v[70:71], v[70:71], v[70:71] op_sel:[0,1] op_sel_hi:[1,0]
	v_pk_fma_f32 v[72:73], v[88:89], v[88:89], v[72:73] op_sel_hi:[1,1,0]
	v_pk_mul_f32 v[76:77], v[84:85], v[84:85]
	v_mov_b32_e32 v73, v78
	v_mov_b32_e32 v69, v76
	v_mov_b32_e32 v71, v77
	v_pk_add_f32 v[68:69], v[68:69], v[70:71]
	v_pk_add_f32 v[70:71], v[72:73], v[74:75]
	flat_store_dwordx2 v[82:83], v[80:81]
	v_pk_add_f32 v[68:69], v[68:69], v[70:71]
	v_pk_mul_f32 v[76:77], v[52:53], v[52:53]
	v_add_f32_e32 v68, v68, v69
	ds_bpermute_b32 v69, v101, v68
	v_pk_mul_f32 v[78:79], v[54:55], v[54:55]
	v_cvt_f32_f16_sdwa v37, v38 dst_sel:DWORD dst_unused:UNUSED_PAD src0_sel:WORD_1
	v_cvt_f32_f16_e32 v38, v39
	v_cvt_f32_f16_sdwa v39, v39 dst_sel:DWORD dst_unused:UNUSED_PAD src0_sel:WORD_1
	s_waitcnt lgkmcnt(0)
	v_add_f32_e32 v68, v68, v69
	ds_bpermute_b32 v69, v102, v68
	s_waitcnt lgkmcnt(0)
	v_add_f32_e32 v68, v68, v69
	ds_bpermute_b32 v69, v103, v68
	s_waitcnt lgkmcnt(0)
	v_add_f32_e32 v68, v68, v69
	ds_bpermute_b32 v69, v104, v68
	s_waitcnt lgkmcnt(0)
	v_add_f32_e32 v68, v68, v69
	ds_bpermute_b32 v69, v105, v68
	s_waitcnt lgkmcnt(0)
	v_add_f32_e32 v68, v68, v69
	ds_bpermute_b32 v69, v106, v68
	s_waitcnt lgkmcnt(0)
	v_add_f32_e32 v68, v68, v69
	v_fmamk_f32 v68, v68, 0x3a800000, v228
	v_cmp_gt_f32_e32 vcc, s89, v68
	v_mul_f32_e32 v69, 0x4f800000, v68
	s_nop 0
	v_cndmask_b32_e32 v68, v68, v69, vcc
	v_sqrt_f32_e32 v69, v68
	s_nop 0
	v_add_u32_e32 v70, -1, v69
	v_fma_f32 v71, -v70, v69, v68
	v_cmp_ge_f32_e64 s[0:1], 0, v71
	v_add_u32_e32 v71, 1, v69
	s_nop 0
	v_cndmask_b32_e64 v70, v69, v70, s[0:1]
	v_fma_f32 v69, -v71, v69, v68
	v_cmp_lt_f32_e64 s[0:1], 0, v69
	s_nop 1
	v_cndmask_b32_e64 v69, v70, v71, s[0:1]
	v_mul_f32_e32 v70, 0x37800000, v69
	v_cndmask_b32_e32 v69, v69, v70, vcc
	v_cmp_class_f32_e32 vcc, v68, v229
	s_nop 1
	v_cndmask_b32_e32 v68, v69, v68, vcc
	v_div_scale_f32 v69, s[0:1], v68, v68, 1.0
	v_rcp_f32_e32 v70, v69
	s_nop 0
	v_fma_f32 v71, -v69, v70, 1.0
	v_fmac_f32_e32 v70, v71, v70
	v_div_scale_f32 v71, vcc, 1.0, v68, 1.0
	v_mul_f32_e32 v72, v71, v70
	v_fma_f32 v73, -v69, v72, v71
	v_fmac_f32_e32 v72, v73, v70
	v_fma_f32 v69, -v69, v72, v71
	v_div_fmas_f32 v69, v69, v70, v72
	v_div_fixup_f32 v68, v69, v68, 1.0
	v_pk_mul_f32 v[72:73], v[96:97], v[68:69] op_sel_hi:[1,0]
	v_pk_mul_f32 v[74:75], v[98:99], v[68:69] op_sel_hi:[1,0]
	v_pk_fma_f32 v[72:73], v[18:19], v[72:73], v[0:1]
	v_pk_fma_f32 v[74:75], v[16:17], v[74:75], v[2:3]
	v_lshl_add_u64 v[70:71], v[34:35], 0, s[42:43]
	v_cvt_pk_bf16_f32 v72, v72, v73
	v_cvt_pk_bf16_f32 v73, v74, v75
	flat_store_dwordx2 v[70:71], v[72:73]
	v_pk_mul_f32 v[72:73], v[92:93], v[68:69] op_sel_hi:[1,0]
	v_pk_mul_f32 v[74:75], v[94:95], v[68:69] op_sel_hi:[1,0]
	v_pk_fma_f32 v[72:73], v[22:23], v[72:73], v[4:5]
	v_pk_fma_f32 v[74:75], v[20:21], v[74:75], v[6:7]
	v_cvt_pk_bf16_f32 v72, v72, v73
	v_cvt_pk_bf16_f32 v73, v74, v75
	flat_store_dwordx2 v[70:71], v[72:73] offset:512
	v_pk_mul_f32 v[72:73], v[88:89], v[68:69] op_sel_hi:[1,0]
	v_pk_mul_f32 v[74:75], v[90:91], v[68:69] op_sel_hi:[1,0]
	v_pk_fma_f32 v[72:73], v[26:27], v[72:73], v[8:9]
	v_pk_fma_f32 v[74:75], v[24:25], v[74:75], v[10:11]
	v_cvt_pk_bf16_f32 v72, v72, v73
	v_cvt_pk_bf16_f32 v73, v74, v75
	flat_store_dwordx2 v[70:71], v[72:73] offset:1024
	v_pk_mul_f32 v[72:73], v[84:85], v[68:69] op_sel_hi:[1,0]
	v_pk_mul_f32 v[68:69], v[86:87], v[68:69] op_sel_hi:[1,0]
	v_pk_fma_f32 v[72:73], v[30:31], v[72:73], v[12:13]
	v_pk_fma_f32 v[68:69], v[28:29], v[68:69], v[14:15]
	v_cvt_pk_bf16_f32 v72, v72, v73
	v_cvt_pk_bf16_f32 v73, v68, v69
	flat_store_dwordx2 v[70:71], v[72:73] offset:1536
	v_mov_b32_e32 v70, v65
	v_mov_b32_e32 v71, v67
	v_mov_b32_e32 v68, v64
	v_mov_b32_e32 v69, v66
	v_pk_mul_f32 v[70:71], v[70:71], v[70:71]
	v_mov_b32_e32 v72, v61
	v_mov_b32_e32 v73, v63
	v_pk_fma_f32 v[68:69], v[68:69], v[68:69], v[70:71]
	v_mov_b32_e32 v70, v60
	v_mov_b32_e32 v71, v62
	v_pk_mul_f32 v[72:73], v[72:73], v[72:73]
	v_mul_f32_e32 v74, v59, v59
	v_pk_fma_f32 v[70:71], v[70:71], v[70:71], v[72:73]
	v_mul_f32_e32 v72, v57, v57
	v_pk_add_f32 v[68:69], v[68:69], v[68:69] op_sel:[0,1] op_sel_hi:[1,0]
	v_pk_add_f32 v[70:71], v[70:71], v[70:71] op_sel:[0,1] op_sel_hi:[1,0]
	v_pk_fma_f32 v[72:73], v[56:57], v[56:57], v[72:73] op_sel_hi:[1,1,0]
	v_pk_fma_f32 v[74:75], v[58:59], v[58:59], v[74:75] op_sel_hi:[1,1,0]
	v_mov_b32_e32 v69, v76
	v_mov_b32_e32 v71, v77
	v_mov_b32_e32 v73, v78
	v_mov_b32_e32 v75, v79
	v_pk_add_f32 v[68:69], v[68:69], v[70:71]
	v_pk_add_f32 v[70:71], v[72:73], v[74:75]
	s_nop 0
	v_pk_add_f32 v[68:69], v[68:69], v[70:71]
	s_nop 0
	v_add_f32_e32 v68, v68, v69
	ds_bpermute_b32 v69, v101, v68
	s_waitcnt lgkmcnt(0)
	v_add_f32_e32 v68, v68, v69
	ds_bpermute_b32 v69, v102, v68
	s_waitcnt lgkmcnt(0)
	v_add_f32_e32 v68, v68, v69
	ds_bpermute_b32 v69, v103, v68
	s_waitcnt lgkmcnt(0)
	v_add_f32_e32 v68, v68, v69
	ds_bpermute_b32 v69, v104, v68
	s_waitcnt lgkmcnt(0)
	v_add_f32_e32 v68, v68, v69
	ds_bpermute_b32 v69, v105, v68
	s_waitcnt lgkmcnt(0)
	v_add_f32_e32 v68, v68, v69
	ds_bpermute_b32 v69, v106, v68
	s_waitcnt lgkmcnt(0)
	v_add_f32_e32 v68, v68, v69
	v_fmamk_f32 v68, v68, 0x3a800000, v228
	v_cmp_gt_f32_e32 vcc, s89, v68
	v_mul_f32_e32 v69, 0x4f800000, v68
	s_nop 0
	v_cndmask_b32_e32 v68, v68, v69, vcc
	v_sqrt_f32_e32 v69, v68
	s_nop 0
	v_add_u32_e32 v70, -1, v69
	v_fma_f32 v71, -v70, v69, v68
	v_cmp_ge_f32_e64 s[0:1], 0, v71
	v_add_u32_e32 v71, 1, v69
	s_nop 0
	v_cndmask_b32_e64 v70, v69, v70, s[0:1]
	v_fma_f32 v69, -v71, v69, v68
	v_cmp_lt_f32_e64 s[0:1], 0, v69
	s_nop 1
	v_cndmask_b32_e64 v69, v70, v71, s[0:1]
	v_mul_f32_e32 v70, 0x37800000, v69
	v_cndmask_b32_e32 v69, v69, v70, vcc
	v_cmp_class_f32_e32 vcc, v68, v229
	s_nop 1
	v_cndmask_b32_e32 v68, v69, v68, vcc
	v_div_scale_f32 v69, s[0:1], v68, v68, 1.0
	v_rcp_f32_e32 v70, v69
	s_nop 0
	v_fma_f32 v71, -v69, v70, 1.0
	v_fmac_f32_e32 v70, v71, v70
	v_div_scale_f32 v71, vcc, 1.0, v68, 1.0
	v_mul_f32_e32 v72, v71, v70
	v_fma_f32 v73, -v69, v72, v71
	v_fmac_f32_e32 v72, v73, v70
	v_fma_f32 v69, -v69, v72, v71
	v_div_fmas_f32 v69, v69, v70, v72
	v_div_fixup_f32 v68, v69, v68, 1.0
	v_pk_mul_f32 v[56:57], v[56:57], v[68:69] op_sel_hi:[1,0]
	v_pk_mul_f32 v[58:59], v[58:59], v[68:69] op_sel_hi:[1,0]
	v_pk_mul_f32 v[52:53], v[52:53], v[68:69] op_sel_hi:[1,0]
	v_pk_mul_f32 v[54:55], v[54:55], v[68:69] op_sel_hi:[1,0]
	v_pk_fma_f32 v[58:59], v[24:25], v[58:59], v[10:11]
	v_pk_fma_f32 v[56:57], v[26:27], v[56:57], v[8:9]
	v_pk_fma_f32 v[54:55], v[28:29], v[54:55], v[14:15]
	v_pk_fma_f32 v[52:53], v[30:31], v[52:53], v[12:13]
	v_lshl_add_u64 v[70:71], v[34:35], 0, s[36:37]
	v_cvt_pk_bf16_f32 v56, v56, v57
	v_cvt_pk_bf16_f32 v57, v58, v59
	v_cvt_pk_bf16_f32 v52, v52, v53
	v_cvt_pk_bf16_f32 v53, v54, v55
	v_mov_b32_e32 v54, v49
	v_mov_b32_e32 v55, v51
	v_pk_mul_f32 v[60:61], v[60:61], v[68:69] op_sel_hi:[1,0]
	v_pk_mul_f32 v[62:63], v[62:63], v[68:69] op_sel_hi:[1,0]
	flat_store_dwordx2 v[70:71], v[56:57] offset:1024
	flat_store_dwordx2 v[70:71], v[52:53] offset:1536
	v_mov_b32_e32 v52, v48
	v_mov_b32_e32 v53, v50
	v_pk_mul_f32 v[54:55], v[54:55], v[54:55]
	v_mov_b32_e32 v56, v45
	v_mov_b32_e32 v57, v47
	v_pk_fma_f32 v[62:63], v[20:21], v[62:63], v[6:7]
	v_pk_fma_f32 v[60:61], v[22:23], v[60:61], v[4:5]
	v_pk_fma_f32 v[52:53], v[52:53], v[52:53], v[54:55]
	v_mov_b32_e32 v54, v44
	v_mov_b32_e32 v55, v46
	v_pk_mul_f32 v[56:57], v[56:57], v[56:57]
	v_cvt_pk_bf16_f32 v60, v60, v61
	v_cvt_pk_bf16_f32 v61, v62, v63
	v_pk_fma_f32 v[54:55], v[54:55], v[54:55], v[56:57]
	v_mul_f32_e32 v56, v41, v41
	v_mul_f32_e32 v58, v43, v43
	flat_store_dwordx2 v[70:71], v[60:61] offset:512
	v_pk_add_f32 v[52:53], v[52:53], v[52:53] op_sel:[0,1] op_sel_hi:[1,0]
	v_pk_add_f32 v[54:55], v[54:55], v[54:55] op_sel:[0,1] op_sel_hi:[1,0]
	v_pk_fma_f32 v[56:57], v[40:41], v[40:41], v[56:57] op_sel_hi:[1,1,0]
	v_pk_fma_f32 v[58:59], v[42:43], v[42:43], v[58:59] op_sel_hi:[1,1,0]
	v_pk_mul_f32 v[60:61], v[36:37], v[36:37]
	v_pk_mul_f32 v[62:63], v[38:39], v[38:39]
	v_mov_b32_e32 v53, v60
	v_mov_b32_e32 v55, v61
	v_mov_b32_e32 v57, v62
	v_mov_b32_e32 v59, v63
	v_pk_add_f32 v[52:53], v[52:53], v[54:55]
	v_pk_add_f32 v[54:55], v[56:57], v[58:59]
	v_pk_mul_f32 v[64:65], v[64:65], v[68:69] op_sel_hi:[1,0]
	v_pk_add_f32 v[52:53], v[52:53], v[54:55]
	v_pk_mul_f32 v[66:67], v[66:67], v[68:69] op_sel_hi:[1,0]
	v_add_f32_e32 v52, v52, v53
	ds_bpermute_b32 v53, v101, v52
	v_pk_fma_f32 v[66:67], v[16:17], v[66:67], v[2:3]
	v_pk_fma_f32 v[64:65], v[18:19], v[64:65], v[0:1]
	s_waitcnt lgkmcnt(0)
	v_add_f32_e32 v52, v52, v53
	ds_bpermute_b32 v53, v102, v52
	v_cvt_pk_bf16_f32 v64, v64, v65
	v_cvt_pk_bf16_f32 v65, v66, v67
	flat_store_dwordx2 v[70:71], v[64:65]
	s_waitcnt lgkmcnt(0)
	v_add_f32_e32 v52, v52, v53
	ds_bpermute_b32 v53, v103, v52
	s_waitcnt lgkmcnt(0)
	v_add_f32_e32 v52, v52, v53
	ds_bpermute_b32 v53, v104, v52
	s_waitcnt lgkmcnt(0)
	v_add_f32_e32 v52, v52, v53
	ds_bpermute_b32 v53, v105, v52
	s_waitcnt lgkmcnt(0)
	v_add_f32_e32 v52, v52, v53
	ds_bpermute_b32 v53, v106, v52
	s_waitcnt lgkmcnt(0)
	v_add_f32_e32 v52, v52, v53
	v_fmamk_f32 v52, v52, 0x3a800000, v228
	v_cmp_gt_f32_e32 vcc, s89, v52
	v_mul_f32_e32 v53, 0x4f800000, v52
	s_nop 0
	v_cndmask_b32_e32 v52, v52, v53, vcc
	v_sqrt_f32_e32 v53, v52
	s_nop 0
	v_add_u32_e32 v54, -1, v53
	v_fma_f32 v55, -v54, v53, v52
	v_cmp_ge_f32_e64 s[0:1], 0, v55
	v_add_u32_e32 v55, 1, v53
	s_nop 0
	v_cndmask_b32_e64 v54, v53, v54, s[0:1]
	v_fma_f32 v53, -v55, v53, v52
	v_cmp_lt_f32_e64 s[0:1], 0, v53
	s_nop 1
	v_cndmask_b32_e64 v53, v54, v55, s[0:1]
	v_mul_f32_e32 v54, 0x37800000, v53
	v_cndmask_b32_e32 v53, v53, v54, vcc
	v_cmp_class_f32_e32 vcc, v52, v229
	s_nop 1
	v_cndmask_b32_e32 v52, v53, v52, vcc
	v_div_scale_f32 v53, s[0:1], v52, v52, 1.0
	v_rcp_f32_e32 v54, v53
	s_nop 0
	v_fma_f32 v55, -v53, v54, 1.0
	v_fmac_f32_e32 v54, v55, v54
	v_div_scale_f32 v55, vcc, 1.0, v52, 1.0
	v_mul_f32_e32 v56, v55, v54
	v_fma_f32 v57, -v53, v56, v55
	v_fmac_f32_e32 v56, v57, v54
	v_fma_f32 v53, -v53, v56, v55
	v_div_fmas_f32 v53, v53, v54, v56
	v_div_fixup_f32 v52, v53, v52, 1.0
	v_pk_mul_f32 v[48:49], v[48:49], v[52:53] op_sel_hi:[1,0]
	v_pk_mul_f32 v[50:51], v[50:51], v[52:53] op_sel_hi:[1,0]
	v_pk_mul_f32 v[44:45], v[44:45], v[52:53] op_sel_hi:[1,0]
	v_pk_mul_f32 v[46:47], v[46:47], v[52:53] op_sel_hi:[1,0]
	v_pk_mul_f32 v[40:41], v[40:41], v[52:53] op_sel_hi:[1,0]
	v_pk_mul_f32 v[42:43], v[42:43], v[52:53] op_sel_hi:[1,0]
	v_pk_mul_f32 v[36:37], v[36:37], v[52:53] op_sel_hi:[1,0]
	v_pk_mul_f32 v[38:39], v[38:39], v[52:53] op_sel_hi:[1,0]
	v_pk_fma_f32 v[50:51], v[16:17], v[50:51], v[2:3]
	v_pk_fma_f32 v[48:49], v[18:19], v[48:49], v[0:1]
	v_pk_fma_f32 v[46:47], v[20:21], v[46:47], v[6:7]
	v_pk_fma_f32 v[44:45], v[22:23], v[44:45], v[4:5]
	v_pk_fma_f32 v[42:43], v[24:25], v[42:43], v[10:11]
	v_pk_fma_f32 v[40:41], v[26:27], v[40:41], v[8:9]
	v_pk_fma_f32 v[38:39], v[28:29], v[38:39], v[14:15]
	v_pk_fma_f32 v[36:37], v[30:31], v[36:37], v[12:13]
	v_lshl_add_u64 v[54:55], v[34:35], 0, s[34:35]
	v_cvt_pk_bf16_f32 v48, v48, v49
	v_cvt_pk_bf16_f32 v49, v50, v51
	v_cvt_pk_bf16_f32 v44, v44, v45
	v_cvt_pk_bf16_f32 v45, v46, v47
	v_cvt_pk_bf16_f32 v40, v40, v41
	v_cvt_pk_bf16_f32 v41, v42, v43
	v_cvt_pk_bf16_f32 v36, v36, v37
	v_cvt_pk_bf16_f32 v37, v38, v39
	flat_store_dwordx2 v[54:55], v[48:49]
	flat_store_dwordx2 v[54:55], v[44:45] offset:512
	flat_store_dwordx2 v[54:55], v[40:41] offset:1024
	flat_store_dwordx2 v[54:55], v[36:37] offset:1536
	s_cbranch_scc0 .LBB0_789
	v_readlane_b32 s10, v253, 44
	v_readlane_b32 s12, v253, 42
	v_readlane_b32 s14, v253, 40
	v_readlane_b32 s16, v253, 38
	v_readlane_b32 s11, v253, 45
	v_readlane_b32 s13, v253, 43
	v_readlane_b32 s15, v253, 41
	v_readlane_b32 s17, v253, 39
